# bundle16 + counted vmcnt waits at first consumer (lever 1) in the P7 gate hooks and the P2/P7/P8/P11 epilogue residual loads instead of vmcnt(0)
# speedup vs baseline: 1.0042x; 1.0006x over previous
.LBB0_382:
	s_lshl_b32 s56, s79, 8
	s_add_i32 s56, s56, s70
	v_or_b32_e32 v198, s56, v179
	v_lshl_or_b32 v196, s80, 8, v207
	v_ashrrev_i32_e32 v199, 31, v198
	v_ashrrev_i32_e32 v197, 31, v196
	v_lshlrev_b64 v[130:131], 11, v[198:199]
	v_lshl_add_u64 v[228:229], v[130:131], 0, v[196:197]
	v_lshl_add_u64 v[130:131], v[228:229], 2, s[68:69]
	global_load_dwordx4 v[212:215], v[130:131], off offset:16
	global_load_dwordx4 v[216:219], v[130:131], off
	global_load_dwordx4 v[220:223], v[130:131], off offset:528
	global_load_dwordx4 v[224:227], v[130:131], off offset:512
	v_or_b32_e32 v130, 16, v198
	v_ashrrev_i32_e32 v131, 31, v130
	v_lshlrev_b64 v[130:131], 11, v[130:131]
	v_lshl_add_u64 v[204:205], v[130:131], 0, v[196:197]
	v_lshl_add_u64 v[130:131], v[204:205], 2, s[68:69]
	global_load_dwordx4 v[170:173], v[130:131], off offset:16
	global_load_dwordx4 v[174:177], v[130:131], off
	global_load_dwordx4 v[162:165], v[130:131], off offset:528
	global_load_dwordx4 v[166:169], v[130:131], off offset:512
	v_or_b32_e32 v130, 32, v198
	v_ashrrev_i32_e32 v131, 31, v130
	v_lshlrev_b64 v[130:131], 11, v[130:131]
	v_lshl_add_u64 v[202:203], v[130:131], 0, v[196:197]
	v_lshl_add_u64 v[130:131], v[202:203], 2, s[68:69]
	global_load_dwordx4 v[154:157], v[130:131], off offset:16
	global_load_dwordx4 v[158:161], v[130:131], off
	global_load_dwordx4 v[146:149], v[130:131], off offset:528
	global_load_dwordx4 v[150:153], v[130:131], off offset:512
	v_or_b32_e32 v130, 48, v198
	v_ashrrev_i32_e32 v131, 31, v130
	v_lshlrev_b64 v[130:131], 11, v[130:131]
	v_lshl_add_u64 v[200:201], v[130:131], 0, v[196:197]
	v_lshl_add_u64 v[134:135], v[200:201], 2, s[68:69]
	global_load_dwordx4 v[138:141], v[134:135], off offset:16
	global_load_dwordx4 v[142:145], v[134:135], off
	global_load_dwordx4 v[130:133], v[134:135], off offset:528
	s_nop 0
	global_load_dwordx4 v[134:137], v[134:135], off offset:512
	v_lshlrev_b64 v[228:229], 1, v[228:229]
	v_cndmask_b32_e64 v1, 0, 1, s[40:41]
	v_lshl_add_u64 v[230:231], s[14:15], 0, v[228:229]
	v_or_b32_e32 v228, 0x100, v228
	v_cmp_ne_u32_e64 s[12:13], 1, v1
	v_lshl_add_u64 v[228:229], s[14:15], 0, v[228:229]
	s_andn2_b64 vcc, exec, s[40:41]
	v_pk_fma_f32 v[124:125], v[124:125], 0.5, v[214:215] op_sel_hi:[1,0,1]
	v_pk_fma_f32 v[128:129], v[128:129], 0.5, v[218:219] op_sel_hi:[1,0,1]
	v_pk_fma_f32 v[126:127], v[126:127], 0.5, v[216:217] op_sel_hi:[1,0,1]
	v_pk_fma_f32 v[122:123], v[122:123], 0.5, v[212:213] op_sel_hi:[1,0,1]
	v_pk_fma_f32 v[120:121], v[120:121], 0.5, v[226:227] op_sel_hi:[1,0,1]
	v_pk_fma_f32 v[118:119], v[118:119], 0.5, v[224:225] op_sel_hi:[1,0,1]
	v_pk_fma_f32 v[116:117], v[116:117], 0.5, v[222:223] op_sel_hi:[1,0,1]
	v_pk_fma_f32 v[114:115], v[114:115], 0.5, v[220:221] op_sel_hi:[1,0,1]
	s_waitcnt vmcnt(15)
	v_cvt_pk_bf16_f32 v212, v126, v127
	v_cvt_pk_bf16_f32 v213, v128, v129
	v_cvt_pk_bf16_f32 v214, v122, v123
	v_cvt_pk_bf16_f32 v215, v124, v125
	global_store_dwordx4 v[230:231], v[212:215], off
	s_nop 0
	s_nop 1
	v_cvt_pk_bf16_f32 v212, v118, v119
	v_cvt_pk_bf16_f32 v213, v120, v121
	v_cvt_pk_bf16_f32 v214, v114, v115
	v_cvt_pk_bf16_f32 v215, v116, v117
	global_store_dwordx4 v[228:229], v[212:215], off
	s_waitcnt vmcnt(2)
	s_cbranch_vccnz .LBB0_384
	s_nop 0
	v_mov_b32_e32 v212, v126
	v_mov_b32_e32 v126, v129
	v_mov_b32_e32 v129, v120
	v_mov_b32_e32 v213, v118
	v_mov_b32_e32 v118, v127
	v_mov_b32_e32 v127, v121
	v_pk_mul_f32 v[120:121], v[128:129], v[128:129]
	v_mov_b32_e32 v128, v125
	v_mov_b32_e32 v125, v116
	v_mov_b32_e32 v129, v117
	v_pk_mul_f32 v[116:117], v[124:125], v[124:125]
	v_mov_b32_e32 v124, v123
	v_mov_b32_e32 v123, v114
	v_pk_mul_f32 v[118:119], v[118:119], v[118:119]
	v_mov_b32_e32 v125, v115
	v_pk_mul_f32 v[114:115], v[122:123], v[122:123]
	v_pk_fma_f32 v[118:119], v[212:213], v[212:213], v[118:119]
	v_pk_fma_f32 v[120:121], v[126:127], v[126:127], v[120:121]
	v_pk_fma_f32 v[114:115], v[124:125], v[124:125], v[114:115]
	v_pk_fma_f32 v[116:117], v[128:129], v[128:129], v[116:117]
	v_pk_add_f32 v[118:119], v[118:119], v[120:121]
	v_pk_add_f32 v[114:115], v[116:117], v[114:115]
	s_nop 0
	v_pk_add_f32 v[114:115], v[118:119], v[114:115]
	s_nop 0
	v_add_f32_e32 v1, v114, v115
	v_and_b32_e32 v115, 64, v211
	v_xor_b32_e32 v114, 16, v211
	v_add_u32_e32 v115, 64, v115
	v_cmp_lt_i32_e32 vcc, v114, v115
	s_nop 1
	v_cndmask_b32_e32 v114, v211, v114, vcc
	v_lshlrev_b32_e32 v114, 2, v114
	ds_bpermute_b32 v114, v114, v1
	s_waitcnt lgkmcnt(0)
	v_add_f32_e32 v1, v1, v114
	v_xor_b32_e32 v114, 32, v211
	v_cmp_lt_i32_e32 vcc, v114, v115
	s_nop 1
	v_cndmask_b32_e32 v114, v211, v114, vcc
	v_lshlrev_b32_e32 v114, 2, v114
	ds_bpermute_b32 v114, v114, v1
	s_waitcnt lgkmcnt(0)
	v_add_f32_e32 v1, v1, v114
	v_cndmask_b32_e64 v116, 0, v1, s[2:3]
	s_branch .LBB0_385

.LBB0_1326:
	s_andn2_b64 vcc, exec, s[40:41]
	s_cbranch_vccnz .LBB0_1328
	s_cmpk_eq_i32 s38, 0x400
	v_mov_b32_e32 v1, v194
	v_mov_b32_e32 v3, v195
	s_cselect_b32 s40, 0, 0x1000
	s_add_u32 s40, s6, s40
	v_lshl_add_u32 v4, v3, 3, s64
	v_ashrrev_i32_e32 v5, 31, v4
	s_addc_u32 s41, s7, 0
	v_add_u32_e32 v3, s65, v1
	v_lshl_add_u64 v[4:5], v[4:5], 1, s[40:41]
	v_mad_i64_i32 v[134:135], s[40:41], v3, s57, v[4:5]
	v_add_co_u32_e32 v136, vcc, s56, v134
	global_load_dwordx4 v[200:203], v[134:135], off
	s_nop 0
	v_addc_co_u32_e32 v137, vcc, 0, v135, vcc
	global_load_dwordx4 v[204:207], v[136:137], off
	global_load_dwordx4 v[208:211], v[136:137], off offset:256
	global_load_dwordx4 v[212:215], v[134:135], off offset:256
	v_add_u32_e32 v1, 16, v3
	v_add_u32_e32 v134, 32, v3
	v_add_u32_e32 v135, 48, v3
	v_mad_i64_i32 v[138:139], s[40:41], v1, s57, v[4:5]
	v_mad_i64_i32 v[140:141], s[40:41], v134, s57, v[4:5]
	v_mad_i64_i32 v[146:147], s[40:41], v135, s57, v[4:5]
	global_load_dwordx4 v[216:219], v[138:139], off
	global_load_dwordx4 v[166:169], v[138:139], off offset:256
	global_load_dwordx4 v[158:161], v[140:141], off
	global_load_dwordx4 v[150:153], v[140:141], off offset:256
	global_load_dwordx4 v[142:145], v[146:147], off
	global_load_dwordx4 v[134:137], v[146:147], off offset:256
	v_add_co_u32_e32 v138, vcc, s56, v138
	s_nop 1
	v_addc_co_u32_e32 v139, vcc, 0, v139, vcc
	global_load_dwordx4 v[220:223], v[138:139], off
	global_load_dwordx4 v[170:173], v[138:139], off offset:256
	v_add_co_u32_e32 v140, vcc, s56, v140
	s_nop 1
	v_addc_co_u32_e32 v141, vcc, 0, v141, vcc
	global_load_dwordx4 v[162:165], v[140:141], off
	global_load_dwordx4 v[154:157], v[140:141], off offset:256
	v_add_co_u32_e32 v138, vcc, s56, v146
	s_nop 1
	v_addc_co_u32_e32 v139, vcc, 0, v147, vcc
	global_load_dwordx4 v[146:149], v[138:139], off
	s_nop 0
	global_load_dwordx4 v[138:141], v[138:139], off offset:256
	s_waitcnt vmcnt(6)
	v_lshlrev_b32_e32 v226, 16, v202
	v_and_b32_e32 v228, 0xffff0000, v204
	v_and_b32_e32 v230, 0xffff0000, v205
	v_lshlrev_b32_e32 v231, 16, v206
	v_lshlrev_b32_e32 v233, 16, v207
	v_and_b32_e32 v234, 0xffff0000, v207
	v_lshlrev_b32_e32 v229, 16, v205
	v_rcp_f32_e32 v205, v228
	v_rcp_f32_e32 v207, v230
	v_rcp_f32_e32 v228, v231
	v_rcp_f32_e32 v230, v233
	v_rcp_f32_e32 v231, v234
	v_and_b32_e32 v227, 0xffff0000, v202
	v_lshlrev_b32_e32 v202, 16, v203
	v_and_b32_e32 v203, 0xffff0000, v203
	v_lshlrev_b32_e32 v1, 16, v204
	v_rcp_f32_e32 v204, v1
	v_pk_mul_f32 v[202:203], v[230:231], v[202:203]
	v_lshlrev_b32_e32 v1, 16, v209
	v_pk_mul_f32 v[128:129], v[128:129], v[202:203]
	v_rcp_f32_e32 v202, v1
	v_and_b32_e32 v1, 0xffff0000, v209
	v_rcp_f32_e32 v203, v1
	v_lshlrev_b32_e32 v224, 16, v200
	v_and_b32_e32 v225, 0xffff0000, v200
	v_and_b32_e32 v232, 0xffff0000, v206
	v_rcp_f32_e32 v206, v229
	v_lshlrev_b32_e32 v235, 16, v208
	v_and_b32_e32 v208, 0xffff0000, v208
	v_pk_mul_f32 v[204:205], v[204:205], v[224:225]
	v_rcp_f32_e32 v229, v232
	v_rcp_f32_e32 v232, v235
	v_rcp_f32_e32 v233, v208
	v_pk_mul_f32 v[130:131], v[130:131], v[204:205]
	v_lshlrev_b32_e32 v204, 16, v213
	v_and_b32_e32 v205, 0xffff0000, v213
	v_lshlrev_b32_e32 v1, 16, v210
	v_lshlrev_b32_e32 v200, 16, v201
	v_and_b32_e32 v201, 0xffff0000, v201
	v_pk_mul_f32 v[202:203], v[202:203], v[204:205]
	v_rcp_f32_e32 v204, v1
	v_and_b32_e32 v1, 0xffff0000, v210
	v_pk_mul_f32 v[200:201], v[206:207], v[200:201]
	v_rcp_f32_e32 v205, v1
	v_lshlrev_b32_e32 v1, 16, v211
	v_pk_mul_f32 v[132:133], v[132:133], v[200:201]
	v_lshlrev_b32_e32 v200, 16, v212
	v_and_b32_e32 v201, 0xffff0000, v212
	v_rcp_f32_e32 v208, v1
	v_and_b32_e32 v1, 0xffff0000, v211
	v_pk_mul_f32 v[206:207], v[228:229], v[226:227]
	v_pk_mul_f32 v[200:201], v[232:233], v[200:201]
	v_rcp_f32_e32 v209, v1
	v_pk_mul_f32 v[126:127], v[126:127], v[206:207]
	v_lshlrev_b32_e32 v206, 16, v214
	v_and_b32_e32 v207, 0xffff0000, v214
	v_pk_mul_f32 v[122:123], v[122:123], v[200:201]
	v_pk_mul_f32 v[204:205], v[204:205], v[206:207]
	v_pk_mul_f32 v[124:125], v[124:125], v[202:203]
	v_pk_mul_f32 v[118:119], v[118:119], v[204:205]
	v_lshlrev_b32_e32 v202, 16, v216
	v_and_b32_e32 v203, 0xffff0000, v216
	v_lshlrev_b32_e32 v206, 16, v215
	v_and_b32_e32 v207, 0xffff0000, v215
	v_pk_mul_f32 v[206:207], v[208:209], v[206:207]
	s_waitcnt vmcnt(5)
	v_lshlrev_b32_e32 v1, 16, v220
	v_rcp_f32_e32 v200, v1
	v_and_b32_e32 v1, 0xffff0000, v220
	v_rcp_f32_e32 v201, v1
	v_lshlrev_b32_e32 v1, 16, v221
	v_rcp_f32_e32 v204, v1
	v_and_b32_e32 v1, 0xffff0000, v221
	v_rcp_f32_e32 v205, v1
	v_pk_mul_f32 v[200:201], v[200:201], v[202:203]
	v_lshlrev_b32_e32 v202, 16, v217
	v_and_b32_e32 v203, 0xffff0000, v217
	v_lshlrev_b32_e32 v1, 16, v222
	v_pk_mul_f32 v[202:203], v[204:205], v[202:203]
	v_rcp_f32_e32 v204, v1
	v_and_b32_e32 v1, 0xffff0000, v222
	v_rcp_f32_e32 v205, v1
	v_lshlrev_b32_e32 v1, 16, v223
	v_rcp_f32_e32 v208, v1
	v_and_b32_e32 v1, 0xffff0000, v223
	v_rcp_f32_e32 v209, v1
	s_waitcnt vmcnt(4)
	v_lshlrev_b32_e32 v1, 16, v170
	v_pk_mul_f32 v[114:115], v[114:115], v[200:201]
	v_rcp_f32_e32 v200, v1
	v_and_b32_e32 v1, 0xffff0000, v170
	v_rcp_f32_e32 v201, v1
	v_lshlrev_b32_e32 v1, 16, v171
	v_rcp_f32_e32 v170, v1
	v_and_b32_e32 v1, 0xffff0000, v171
	v_rcp_f32_e32 v171, v1
	v_pk_mul_f32 v[116:117], v[116:117], v[202:203]
	v_lshlrev_b32_e32 v202, 16, v166
	v_and_b32_e32 v203, 0xffff0000, v166
	v_lshlrev_b32_e32 v166, 16, v167
	v_and_b32_e32 v167, 0xffff0000, v167
	v_lshlrev_b32_e32 v1, 16, v172
	v_pk_mul_f32 v[166:167], v[170:171], v[166:167]
	v_rcp_f32_e32 v170, v1
	v_and_b32_e32 v1, 0xffff0000, v172
	v_rcp_f32_e32 v171, v1
	v_lshlrev_b32_e32 v1, 16, v173
	v_rcp_f32_e32 v172, v1
	v_and_b32_e32 v1, 0xffff0000, v173
	v_rcp_f32_e32 v173, v1
	s_waitcnt vmcnt(3)
	v_lshlrev_b32_e32 v1, 16, v162
	v_pk_mul_f32 v[108:109], v[108:109], v[166:167]
	v_rcp_f32_e32 v166, v1
	v_and_b32_e32 v1, 0xffff0000, v162
	v_rcp_f32_e32 v167, v1
	v_lshlrev_b32_e32 v1, 16, v163
	v_rcp_f32_e32 v162, v1
	v_and_b32_e32 v1, 0xffff0000, v163
	v_rcp_f32_e32 v163, v1
	v_pk_mul_f32 v[200:201], v[200:201], v[202:203]
	v_lshlrev_b32_e32 v202, 16, v168
	v_and_b32_e32 v203, 0xffff0000, v168
	v_lshlrev_b32_e32 v168, 16, v169
	v_and_b32_e32 v169, 0xffff0000, v169
	v_pk_mul_f32 v[168:169], v[172:173], v[168:169]
	v_lshlrev_b32_e32 v1, 16, v164
	v_pk_mul_f32 v[104:105], v[104:105], v[168:169]
	v_lshlrev_b32_e32 v168, 16, v158
	v_and_b32_e32 v169, 0xffff0000, v158
	v_lshlrev_b32_e32 v158, 16, v159
	v_and_b32_e32 v159, 0xffff0000, v159
	v_pk_mul_f32 v[158:159], v[162:163], v[158:159]
	v_rcp_f32_e32 v162, v1
	v_and_b32_e32 v1, 0xffff0000, v164
	v_rcp_f32_e32 v163, v1
	v_lshlrev_b32_e32 v1, 16, v165
	v_rcp_f32_e32 v164, v1
	v_and_b32_e32 v1, 0xffff0000, v165
	v_rcp_f32_e32 v165, v1
	s_waitcnt vmcnt(2)
	v_lshlrev_b32_e32 v1, 16, v154
	v_pk_mul_f32 v[100:101], v[100:101], v[158:159]
	v_rcp_f32_e32 v158, v1
	v_and_b32_e32 v1, 0xffff0000, v154
	v_rcp_f32_e32 v159, v1
	v_lshlrev_b32_e32 v1, 16, v155
	v_rcp_f32_e32 v154, v1
	v_and_b32_e32 v1, 0xffff0000, v155
	v_rcp_f32_e32 v155, v1
	v_pk_mul_f32 v[166:167], v[166:167], v[168:169]
	v_lshlrev_b32_e32 v168, 16, v160
	v_and_b32_e32 v169, 0xffff0000, v160
	v_lshlrev_b32_e32 v160, 16, v161
	v_and_b32_e32 v161, 0xffff0000, v161
	v_pk_mul_f32 v[160:161], v[164:165], v[160:161]
	v_lshlrev_b32_e32 v1, 16, v156
	v_pk_mul_f32 v[96:97], v[96:97], v[160:161]
	v_lshlrev_b32_e32 v160, 16, v150
	v_and_b32_e32 v161, 0xffff0000, v150
	v_lshlrev_b32_e32 v150, 16, v151
	v_and_b32_e32 v151, 0xffff0000, v151
	v_pk_mul_f32 v[150:151], v[154:155], v[150:151]
	v_rcp_f32_e32 v154, v1
	v_and_b32_e32 v1, 0xffff0000, v156
	v_rcp_f32_e32 v155, v1
	v_lshlrev_b32_e32 v1, 16, v157
	v_rcp_f32_e32 v156, v1
	v_and_b32_e32 v1, 0xffff0000, v157
	v_rcp_f32_e32 v157, v1
	s_waitcnt vmcnt(1)
	v_lshlrev_b32_e32 v1, 16, v146
	v_pk_mul_f32 v[92:93], v[92:93], v[150:151]
	v_rcp_f32_e32 v150, v1
	v_and_b32_e32 v1, 0xffff0000, v146
	v_rcp_f32_e32 v151, v1
	v_pk_mul_f32 v[158:159], v[158:159], v[160:161]
	v_lshlrev_b32_e32 v160, 16, v152
	v_and_b32_e32 v161, 0xffff0000, v152
	v_lshlrev_b32_e32 v152, 16, v153
	v_and_b32_e32 v153, 0xffff0000, v153
	v_pk_mul_f32 v[152:153], v[156:157], v[152:153]
	v_pk_mul_f32 v[154:155], v[154:155], v[160:161]
	v_pk_mul_f32 v[88:89], v[88:89], v[152:153]
	v_lshlrev_b32_e32 v152, 16, v142
	v_and_b32_e32 v153, 0xffff0000, v142
	v_pk_mul_f32 v[150:151], v[150:151], v[152:153]
	v_lshlrev_b32_e32 v152, 16, v144
	v_and_b32_e32 v153, 0xffff0000, v144
	v_add_u32_e32 v144, 0x80, v3
	v_pk_mul_f32 v[86:87], v[86:87], v[154:155]
	v_mad_i64_i32 v[154:155], s[40:41], v144, s57, v[4:5]
	v_add_co_u32_e32 v156, vcc, s56, v154
	v_lshlrev_b32_e32 v1, 16, v147
	s_nop 0
	v_addc_co_u32_e32 v157, vcc, 0, v155, vcc
	v_pk_mul_f32 v[170:171], v[170:171], v[202:203]
	v_pk_mul_f32 v[106:107], v[106:107], v[200:201]
	v_rcp_f32_e32 v146, v1
	v_and_b32_e32 v1, 0xffff0000, v147
	global_load_dwordx4 v[200:203], v[156:157], off
	v_rcp_f32_e32 v147, v1
	v_pk_mul_f32 v[120:121], v[120:121], v[206:207]
	v_lshlrev_b32_e32 v206, 16, v218
	v_and_b32_e32 v207, 0xffff0000, v218
	v_lshlrev_b32_e32 v142, 16, v143
	v_and_b32_e32 v143, 0xffff0000, v143
	v_lshlrev_b32_e32 v1, 16, v148
	v_pk_mul_f32 v[204:205], v[204:205], v[206:207]
	v_lshlrev_b32_e32 v206, 16, v219
	v_and_b32_e32 v207, 0xffff0000, v219
	v_pk_mul_f32 v[142:143], v[146:147], v[142:143]
	v_rcp_f32_e32 v146, v1
	v_and_b32_e32 v1, 0xffff0000, v148
	v_pk_mul_f32 v[206:207], v[208:209], v[206:207]
	v_rcp_f32_e32 v147, v1
	v_lshlrev_b32_e32 v1, 16, v149
	v_pk_mul_f32 v[112:113], v[112:113], v[206:207]
	v_pk_mul_f32 v[110:111], v[110:111], v[204:205]
	v_rcp_f32_e32 v148, v1
	v_and_b32_e32 v1, 0xffff0000, v149
	global_load_dwordx4 v[204:207], v[154:155], off
	global_load_dwordx4 v[212:215], v[154:155], off offset:256
	v_rcp_f32_e32 v149, v1
	s_waitcnt vmcnt(3)
	v_lshlrev_b32_e32 v1, 16, v138
	v_pk_mul_f32 v[84:85], v[84:85], v[142:143]
	v_rcp_f32_e32 v142, v1
	v_and_b32_e32 v1, 0xffff0000, v138
	v_rcp_f32_e32 v143, v1
	v_lshlrev_b32_e32 v1, 16, v139
	v_rcp_f32_e32 v138, v1
	v_and_b32_e32 v1, 0xffff0000, v139
	v_rcp_f32_e32 v139, v1
	v_lshlrev_b32_e32 v144, 16, v145
	v_and_b32_e32 v145, 0xffff0000, v145
	global_load_dwordx4 v[208:211], v[156:157], off offset:256
	v_pk_mul_f32 v[144:145], v[148:149], v[144:145]
	v_lshlrev_b32_e32 v1, 16, v140
	v_pk_mul_f32 v[80:81], v[80:81], v[144:145]
	v_lshlrev_b32_e32 v144, 16, v134
	v_and_b32_e32 v145, 0xffff0000, v134
	v_lshlrev_b32_e32 v134, 16, v135
	v_and_b32_e32 v135, 0xffff0000, v135
	v_pk_mul_f32 v[134:135], v[138:139], v[134:135]
	v_rcp_f32_e32 v138, v1
	v_and_b32_e32 v1, 0xffff0000, v140
	v_rcp_f32_e32 v139, v1
	v_lshlrev_b32_e32 v1, 16, v141
	v_rcp_f32_e32 v140, v1
	v_and_b32_e32 v1, 0xffff0000, v141
	v_rcp_f32_e32 v141, v1
	v_pk_mul_f32 v[142:143], v[142:143], v[144:145]
	v_lshlrev_b32_e32 v144, 16, v136
	v_and_b32_e32 v145, 0xffff0000, v136
	v_lshlrev_b32_e32 v136, 16, v137
	v_and_b32_e32 v137, 0xffff0000, v137
	v_add_u32_e32 v1, 0x90, v3
	v_pk_mul_f32 v[136:137], v[140:141], v[136:137]
	v_pk_mul_f32 v[76:77], v[76:77], v[134:135]
	v_mad_i64_i32 v[134:135], s[40:41], v1, s57, v[4:5]
	v_pk_mul_f32 v[72:73], v[72:73], v[136:137]
	v_add_co_u32_e32 v136, vcc, s56, v134
	v_pk_mul_f32 v[102:103], v[102:103], v[170:171]
	v_pk_mul_f32 v[162:163], v[162:163], v[168:169]
	v_pk_mul_f32 v[98:99], v[98:99], v[166:167]
	v_addc_co_u32_e32 v137, vcc, 0, v135, vcc
	global_load_dwordx4 v[216:219], v[134:135], off
	global_load_dwordx4 v[166:169], v[134:135], off offset:256
	global_load_dwordx4 v[220:223], v[136:137], off
	global_load_dwordx4 v[170:173], v[136:137], off offset:256
	v_add_u32_e32 v1, 0xa0, v3
	v_mad_i64_i32 v[134:135], s[40:41], v1, s57, v[4:5]
	v_add_co_u32_e32 v136, vcc, s56, v134
	v_pk_mul_f32 v[94:95], v[94:95], v[162:163]
	v_pk_mul_f32 v[90:91], v[90:91], v[158:159]
	v_pk_mul_f32 v[146:147], v[146:147], v[152:153]
	v_pk_mul_f32 v[82:83], v[82:83], v[150:151]
	v_addc_co_u32_e32 v137, vcc, 0, v135, vcc
	global_load_dwordx4 v[158:161], v[134:135], off
	global_load_dwordx4 v[150:153], v[134:135], off offset:256
	global_load_dwordx4 v[162:165], v[136:137], off
	global_load_dwordx4 v[154:157], v[136:137], off offset:256
	v_add_u32_e32 v1, 0xb0, v3
	v_pk_mul_f32 v[138:139], v[138:139], v[144:145]
	v_mad_i64_i32 v[4:5], s[40:41], v1, s57, v[4:5]
	v_pk_mul_f32 v[70:71], v[70:71], v[138:139]
	v_add_co_u32_e32 v138, vcc, s56, v4
	v_pk_mul_f32 v[78:79], v[78:79], v[146:147]
	s_nop 0
	v_addc_co_u32_e32 v139, vcc, 0, v5, vcc
	v_pk_mul_f32 v[74:75], v[74:75], v[142:143]
	global_load_dwordx4 v[142:145], v[4:5], off
	global_load_dwordx4 v[134:137], v[4:5], off offset:256
	global_load_dwordx4 v[146:149], v[138:139], off
	s_nop 0
	global_load_dwordx4 v[138:141], v[138:139], off offset:256
	s_waitcnt vmcnt(15)
	v_lshlrev_b32_e32 v1, 16, v200
	v_rcp_f32_e32 v4, v1
	v_and_b32_e32 v1, 0xffff0000, v200
	v_rcp_f32_e32 v5, v1
	v_lshlrev_b32_e32 v1, 16, v201
	v_rcp_f32_e32 v200, v1
	v_and_b32_e32 v1, 0xffff0000, v201
	v_rcp_f32_e32 v201, v1
	s_waitcnt vmcnt(14)
	v_lshlrev_b32_e32 v224, 16, v204
	v_and_b32_e32 v225, 0xffff0000, v204
	v_lshlrev_b32_e32 v204, 16, v205
	v_and_b32_e32 v205, 0xffff0000, v205
	v_lshlrev_b32_e32 v1, 16, v202
	v_pk_mul_f32 v[200:201], v[200:201], v[204:205]
	v_rcp_f32_e32 v204, v1
	v_and_b32_e32 v1, 0xffff0000, v202
	v_rcp_f32_e32 v205, v1
	v_lshlrev_b32_e32 v1, 16, v203
	v_rcp_f32_e32 v202, v1
	v_and_b32_e32 v1, 0xffff0000, v203
	v_rcp_f32_e32 v203, v1
	v_pk_mul_f32 v[4:5], v[4:5], v[224:225]
	s_waitcnt vmcnt(12)
	v_lshlrev_b32_e32 v1, 16, v208
	v_lshlrev_b32_e32 v224, 16, v206
	v_and_b32_e32 v225, 0xffff0000, v206
	v_lshlrev_b32_e32 v206, 16, v207
	v_and_b32_e32 v207, 0xffff0000, v207
	v_pk_mul_f32 v[66:67], v[66:67], v[4:5]
	v_rcp_f32_e32 v4, v1
	v_and_b32_e32 v1, 0xffff0000, v208
	v_pk_mul_f32 v[202:203], v[202:203], v[206:207]
	v_rcp_f32_e32 v5, v1
	v_lshlrev_b32_e32 v1, 16, v209
	v_pk_mul_f32 v[64:65], v[64:65], v[202:203]
	v_rcp_f32_e32 v202, v1
	v_and_b32_e32 v1, 0xffff0000, v209
	v_rcp_f32_e32 v203, v1
	v_pk_mul_f32 v[68:69], v[68:69], v[200:201]
	v_lshlrev_b32_e32 v200, 16, v212
	v_and_b32_e32 v201, 0xffff0000, v212
	v_pk_mul_f32 v[4:5], v[4:5], v[200:201]
	v_lshlrev_b32_e32 v200, 16, v213
	v_and_b32_e32 v201, 0xffff0000, v213
	v_lshlrev_b32_e32 v1, 16, v210
	v_pk_mul_f32 v[200:201], v[202:203], v[200:201]
	v_rcp_f32_e32 v202, v1
	v_and_b32_e32 v1, 0xffff0000, v210
	v_rcp_f32_e32 v203, v1
	v_lshlrev_b32_e32 v1, 16, v211
	v_rcp_f32_e32 v206, v1
	v_and_b32_e32 v1, 0xffff0000, v211
	v_pk_mul_f32 v[204:205], v[204:205], v[224:225]
	v_rcp_f32_e32 v207, v1
	v_pk_mul_f32 v[62:63], v[62:63], v[204:205]
	s_waitcnt vmcnt(9)
	v_lshlrev_b32_e32 v1, 16, v220
	v_lshlrev_b32_e32 v204, 16, v214
	v_and_b32_e32 v205, 0xffff0000, v214
	v_pk_mul_f32 v[58:59], v[58:59], v[4:5]
	v_rcp_f32_e32 v4, v1
	v_and_b32_e32 v1, 0xffff0000, v220
	v_pk_mul_f32 v[202:203], v[202:203], v[204:205]
	v_rcp_f32_e32 v5, v1
	v_lshlrev_b32_e32 v1, 16, v221
	v_pk_mul_f32 v[54:55], v[54:55], v[202:203]
	v_rcp_f32_e32 v202, v1
	v_and_b32_e32 v1, 0xffff0000, v221
	v_rcp_f32_e32 v203, v1
	v_pk_mul_f32 v[60:61], v[60:61], v[200:201]
	v_lshlrev_b32_e32 v200, 16, v216
	v_and_b32_e32 v201, 0xffff0000, v216
	v_pk_mul_f32 v[4:5], v[4:5], v[200:201]
	v_lshlrev_b32_e32 v200, 16, v217
	v_and_b32_e32 v201, 0xffff0000, v217
	v_lshlrev_b32_e32 v1, 16, v222
	v_pk_mul_f32 v[200:201], v[202:203], v[200:201]
	v_rcp_f32_e32 v202, v1
	v_and_b32_e32 v1, 0xffff0000, v222
	v_lshlrev_b32_e32 v204, 16, v215
	v_and_b32_e32 v205, 0xffff0000, v215
	v_rcp_f32_e32 v203, v1
	v_lshlrev_b32_e32 v1, 16, v223
	v_pk_mul_f32 v[204:205], v[206:207], v[204:205]
	v_rcp_f32_e32 v206, v1
	v_and_b32_e32 v1, 0xffff0000, v223
	v_rcp_f32_e32 v207, v1
	s_waitcnt vmcnt(8)
	v_lshlrev_b32_e32 v1, 16, v170
	v_pk_mul_f32 v[50:51], v[50:51], v[4:5]
	v_rcp_f32_e32 v4, v1
	v_and_b32_e32 v1, 0xffff0000, v170
	v_rcp_f32_e32 v5, v1
	v_lshlrev_b32_e32 v1, 16, v171
	v_rcp_f32_e32 v170, v1
	v_and_b32_e32 v1, 0xffff0000, v171
	v_rcp_f32_e32 v171, v1
	v_pk_mul_f32 v[52:53], v[52:53], v[200:201]
	v_lshlrev_b32_e32 v200, 16, v166
	v_and_b32_e32 v201, 0xffff0000, v166
	v_lshlrev_b32_e32 v166, 16, v167
	v_and_b32_e32 v167, 0xffff0000, v167
	v_lshlrev_b32_e32 v1, 16, v172
	v_pk_mul_f32 v[166:167], v[170:171], v[166:167]
	v_rcp_f32_e32 v170, v1
	v_and_b32_e32 v1, 0xffff0000, v172
	v_rcp_f32_e32 v171, v1
	v_lshlrev_b32_e32 v1, 16, v173
	v_rcp_f32_e32 v172, v1
	v_and_b32_e32 v1, 0xffff0000, v173
	v_pk_mul_f32 v[4:5], v[4:5], v[200:201]
	v_rcp_f32_e32 v173, v1
	s_waitcnt vmcnt(5)
	v_lshlrev_b32_e32 v1, 16, v162
	v_pk_mul_f32 v[42:43], v[42:43], v[4:5]
	v_rcp_f32_e32 v4, v1
	v_and_b32_e32 v1, 0xffff0000, v162
	v_rcp_f32_e32 v5, v1
	v_lshlrev_b32_e32 v1, 16, v163
	v_rcp_f32_e32 v162, v1
	v_and_b32_e32 v1, 0xffff0000, v163
	v_rcp_f32_e32 v163, v1
	v_pk_mul_f32 v[44:45], v[44:45], v[166:167]
	v_lshlrev_b32_e32 v166, 16, v158
	v_and_b32_e32 v167, 0xffff0000, v158
	v_lshlrev_b32_e32 v158, 16, v159
	v_and_b32_e32 v159, 0xffff0000, v159
	v_lshlrev_b32_e32 v1, 16, v164
	v_pk_mul_f32 v[158:159], v[162:163], v[158:159]
	v_rcp_f32_e32 v162, v1
	v_and_b32_e32 v1, 0xffff0000, v164
	v_rcp_f32_e32 v163, v1
	v_lshlrev_b32_e32 v1, 16, v165
	v_rcp_f32_e32 v164, v1
	v_and_b32_e32 v1, 0xffff0000, v165
	v_pk_mul_f32 v[4:5], v[4:5], v[166:167]
	v_rcp_f32_e32 v165, v1
	s_waitcnt vmcnt(4)
	v_lshlrev_b32_e32 v1, 16, v154
	v_pk_mul_f32 v[34:35], v[34:35], v[4:5]
	v_rcp_f32_e32 v4, v1
	v_and_b32_e32 v1, 0xffff0000, v154
	v_rcp_f32_e32 v5, v1
	v_lshlrev_b32_e32 v1, 16, v155
	v_rcp_f32_e32 v154, v1
	v_and_b32_e32 v1, 0xffff0000, v155
	v_rcp_f32_e32 v155, v1
	v_pk_mul_f32 v[36:37], v[36:37], v[158:159]
	v_lshlrev_b32_e32 v158, 16, v150
	v_and_b32_e32 v159, 0xffff0000, v150
	v_lshlrev_b32_e32 v150, 16, v151
	v_and_b32_e32 v151, 0xffff0000, v151
	v_lshlrev_b32_e32 v1, 16, v156
	v_pk_mul_f32 v[150:151], v[154:155], v[150:151]
	v_rcp_f32_e32 v154, v1
	v_and_b32_e32 v1, 0xffff0000, v156
	v_rcp_f32_e32 v155, v1
	v_lshlrev_b32_e32 v1, 16, v157
	v_rcp_f32_e32 v156, v1
	v_and_b32_e32 v1, 0xffff0000, v157
	v_pk_mul_f32 v[4:5], v[4:5], v[158:159]
	v_rcp_f32_e32 v157, v1
	s_waitcnt vmcnt(1)
	v_lshlrev_b32_e32 v1, 16, v146
	v_pk_mul_f32 v[26:27], v[26:27], v[4:5]
	v_rcp_f32_e32 v4, v1
	v_and_b32_e32 v1, 0xffff0000, v146
	v_rcp_f32_e32 v5, v1
	v_lshlrev_b32_e32 v1, 16, v147
	v_rcp_f32_e32 v146, v1
	v_and_b32_e32 v1, 0xffff0000, v147
	v_rcp_f32_e32 v147, v1
	v_pk_mul_f32 v[28:29], v[28:29], v[150:151]
	v_lshlrev_b32_e32 v150, 16, v142
	v_and_b32_e32 v151, 0xffff0000, v142
	v_lshlrev_b32_e32 v142, 16, v143
	v_and_b32_e32 v143, 0xffff0000, v143
	v_lshlrev_b32_e32 v1, 16, v148
	v_pk_mul_f32 v[142:143], v[146:147], v[142:143]
	v_rcp_f32_e32 v146, v1
	v_and_b32_e32 v1, 0xffff0000, v148
	v_rcp_f32_e32 v147, v1
	v_lshlrev_b32_e32 v1, 16, v149
	v_rcp_f32_e32 v148, v1
	v_and_b32_e32 v1, 0xffff0000, v149
	v_pk_mul_f32 v[4:5], v[4:5], v[150:151]
	v_rcp_f32_e32 v149, v1
	s_waitcnt vmcnt(0)
	v_lshlrev_b32_e32 v1, 16, v138
	v_pk_mul_f32 v[18:19], v[18:19], v[4:5]
	v_rcp_f32_e32 v4, v1
	v_and_b32_e32 v1, 0xffff0000, v138
	v_rcp_f32_e32 v5, v1
	v_lshlrev_b32_e32 v1, 16, v139
	v_rcp_f32_e32 v138, v1
	v_and_b32_e32 v1, 0xffff0000, v139
	v_rcp_f32_e32 v139, v1
	v_pk_mul_f32 v[20:21], v[20:21], v[142:143]
	v_lshlrev_b32_e32 v142, 16, v134
	v_and_b32_e32 v143, 0xffff0000, v134
	v_lshlrev_b32_e32 v134, 16, v135
	v_and_b32_e32 v135, 0xffff0000, v135
	v_lshlrev_b32_e32 v1, 16, v140
	v_pk_mul_f32 v[134:135], v[138:139], v[134:135]
	v_rcp_f32_e32 v138, v1
	v_and_b32_e32 v1, 0xffff0000, v140
	v_rcp_f32_e32 v139, v1
	v_lshlrev_b32_e32 v1, 16, v141
	v_rcp_f32_e32 v140, v1
	v_and_b32_e32 v1, 0xffff0000, v141
	v_rcp_f32_e32 v141, v1
	v_pk_mul_f32 v[56:57], v[56:57], v[204:205]
	v_lshlrev_b32_e32 v204, 16, v218
	v_and_b32_e32 v205, 0xffff0000, v218
	v_pk_mul_f32 v[202:203], v[202:203], v[204:205]
	v_lshlrev_b32_e32 v204, 16, v219
	v_and_b32_e32 v205, 0xffff0000, v219
	v_lshlrev_b32_e32 v200, 16, v168
	v_and_b32_e32 v201, 0xffff0000, v168
	v_lshlrev_b32_e32 v168, 16, v169
	v_and_b32_e32 v169, 0xffff0000, v169
	v_lshlrev_b32_e32 v166, 16, v160
	v_and_b32_e32 v167, 0xffff0000, v160
	v_lshlrev_b32_e32 v160, 16, v161
	v_and_b32_e32 v161, 0xffff0000, v161
	v_lshlrev_b32_e32 v158, 16, v152
	v_and_b32_e32 v159, 0xffff0000, v152
	v_lshlrev_b32_e32 v152, 16, v153
	v_and_b32_e32 v153, 0xffff0000, v153
	v_lshlrev_b32_e32 v150, 16, v144
	v_and_b32_e32 v151, 0xffff0000, v144
	v_lshlrev_b32_e32 v144, 16, v145
	v_and_b32_e32 v145, 0xffff0000, v145
	v_pk_mul_f32 v[4:5], v[4:5], v[142:143]
	v_lshlrev_b32_e32 v142, 16, v136
	v_and_b32_e32 v143, 0xffff0000, v136
	v_lshlrev_b32_e32 v136, 16, v137
	v_and_b32_e32 v137, 0xffff0000, v137
	s_waitcnt vmcnt(0)
	v_pk_mul_f32 v[204:205], v[206:207], v[204:205]
	v_pk_mul_f32 v[170:171], v[170:171], v[200:201]
	v_pk_mul_f32 v[168:169], v[172:173], v[168:169]
	v_pk_mul_f32 v[162:163], v[162:163], v[166:167]
	v_pk_mul_f32 v[160:161], v[164:165], v[160:161]
	v_pk_mul_f32 v[154:155], v[154:155], v[158:159]
	v_pk_mul_f32 v[152:153], v[156:157], v[152:153]
	v_pk_mul_f32 v[146:147], v[146:147], v[150:151]
	v_pk_mul_f32 v[144:145], v[148:149], v[144:145]
	v_pk_mul_f32 v[138:139], v[138:139], v[142:143]
	v_pk_mul_f32 v[136:137], v[140:141], v[136:137]
	v_pk_mul_f32 v[48:49], v[48:49], v[204:205]
	v_pk_mul_f32 v[46:47], v[46:47], v[202:203]
	v_pk_mul_f32 v[40:41], v[40:41], v[168:169]
	v_pk_mul_f32 v[38:39], v[38:39], v[170:171]
	v_pk_mul_f32 v[32:33], v[32:33], v[160:161]
	v_pk_mul_f32 v[30:31], v[30:31], v[162:163]
	v_pk_mul_f32 v[24:25], v[24:25], v[152:153]
	v_pk_mul_f32 v[22:23], v[22:23], v[154:155]
	v_pk_mul_f32 v[16:17], v[16:17], v[144:145]
	v_pk_mul_f32 v[14:15], v[14:15], v[146:147]
	v_pk_mul_f32 v[12:13], v[12:13], v[134:135]
	v_pk_mul_f32 v[10:11], v[10:11], v[4:5]
	v_pk_mul_f32 v[8:9], v[8:9], v[136:137]
	v_pk_mul_f32 v[6:7], v[6:7], v[138:139]

.LBB0_1332:
	v_or_b32_e32 v4, s61, v198
	v_add_u32_e32 v134, s15, v196
	v_ashrrev_i32_e32 v5, 31, v4
	v_mov_b64_e32 v[136:137], s[6:7]
	v_mad_i64_i32 v[138:139], s[36:37], v134, s57, v[136:137]
	v_lshlrev_b64 v[4:5], 1, v[4:5]
	v_lshl_add_u64 v[142:143], v[138:139], 0, v[4:5]
	v_add_co_u32_e32 v138, vcc, 0x2000, v142
	v_or_b32_e32 v170, 16, v134
	s_nop 0
	v_addc_co_u32_e32 v139, vcc, 0, v143, vcc
	global_load_dwordx4 v[138:141], v[138:139], off
	v_lshl_add_u64 v[142:143], v[142:143], 0, s[12:13]
	global_load_dwordx4 v[142:145], v[142:143], off offset:256
	v_mad_i64_i32 v[146:147], s[36:37], v170, s57, v[136:137]
	v_lshl_add_u64 v[150:151], v[146:147], 0, v[4:5]
	v_add_co_u32_e32 v146, vcc, 0x2000, v150
	v_ashrrev_i32_e32 v135, 31, v134
	s_nop 0
	v_addc_co_u32_e32 v147, vcc, 0, v151, vcc
	global_load_dwordx4 v[146:149], v[146:147], off
	v_or_b32_e32 v172, 32, v134
	v_mad_i64_i32 v[152:153], s[36:37], v172, s57, v[136:137]
	v_lshlrev_b64 v[156:157], 12, v[134:135]
	v_lshl_add_u64 v[158:159], v[152:153], 0, v[4:5]
	v_lshl_add_u64 v[152:153], s[4:5], 0, v[156:157]
	v_lshl_add_u64 v[150:151], v[150:151], 0, s[12:13]
	v_lshl_add_u64 v[192:193], v[152:153], 0, v[4:5]
	global_load_dwordx4 v[150:153], v[150:151], off offset:256
	v_or_b32_e32 v190, 48, v134
	v_mad_i64_i32 v[154:155], s[36:37], v190, s57, v[136:137]
	v_lshl_add_u64 v[162:163], v[154:155], 0, v[4:5]
	v_add_co_u32_e32 v154, vcc, 0x2000, v158
	v_lshl_add_u64 v[160:161], v[158:159], 0, s[12:13]
	s_nop 0
	v_addc_co_u32_e32 v155, vcc, 0, v159, vcc
	global_load_dwordx4 v[154:157], v[154:155], off
	s_nop 0
	global_load_dwordx4 v[158:161], v[160:161], off offset:256
	v_lshl_add_u64 v[166:167], v[162:163], 0, s[12:13]
	v_add_co_u32_e32 v162, vcc, 0x2000, v162
	v_ashrrev_i32_e32 v171, 31, v170
	s_nop 0
	v_addc_co_u32_e32 v163, vcc, 0, v163, vcc
	global_load_dwordx4 v[162:165], v[162:163], off
	s_nop 0
	global_load_dwordx4 v[166:169], v[166:167], off offset:256
	v_ashrrev_i32_e32 v173, 31, v172
	v_ashrrev_i32_e32 v191, 31, v190
	s_waitcnt vmcnt(7)
	v_lshlrev_b32_e32 v1, 16, v138
	v_and_b32_e32 v3, 0xffff0000, v138
	v_lshlrev_b32_e32 v135, 16, v139
	s_waitcnt vmcnt(6)
	v_lshlrev_b32_e32 v201, 16, v142
	v_mul_f32_e32 v1, v130, v1
	v_mul_f32_e32 v3, v131, v3
	v_and_b32_e32 v138, 0xffff0000, v139
	v_lshlrev_b32_e32 v139, 16, v140
	v_and_b32_e32 v140, 0xffff0000, v140
	v_and_b32_e32 v142, 0xffff0000, v142
	v_lshlrev_b32_e32 v202, 16, v143
	v_mul_f32_e32 v130, v132, v135
	v_mul_f32_e32 v132, v122, v201
	v_cvt_pk_bf16_f32 v122, v1, v3
	v_lshlrev_b32_e32 v1, 16, v144
	v_and_b32_e32 v3, 0xffff0000, v144
	v_lshlrev_b32_e32 v200, 16, v141
	v_and_b32_e32 v141, 0xffff0000, v141
	v_and_b32_e32 v143, 0xffff0000, v143
	v_mul_f32_e32 v131, v133, v138
	v_mul_f32_e32 v126, v126, v139
	v_mul_f32_e32 v127, v127, v140
	v_mul_f32_e32 v133, v123, v142
	v_mul_f32_e32 v135, v124, v202
	v_cvt_pk_bf16_f32 v123, v130, v131
	v_cvt_pk_bf16_f32 v124, v126, v127
	v_mul_f32_e32 v1, v118, v1
	v_mul_f32_e32 v3, v119, v3
	v_mul_f32_e32 v128, v128, v200
	v_mul_f32_e32 v129, v129, v141
	v_mul_f32_e32 v138, v125, v143
	v_cvt_pk_bf16_f32 v125, v128, v129
	global_store_dwordx4 v[192:193], v[122:125], off
	v_lshlrev_b64 v[118:119], 12, v[170:171]
	s_nop 0
	v_cvt_pk_bf16_f32 v122, v132, v133
	v_cvt_pk_bf16_f32 v123, v135, v138
	v_cvt_pk_bf16_f32 v124, v1, v3
	v_lshlrev_b32_e32 v1, 16, v145
	v_and_b32_e32 v3, 0xffff0000, v145
	v_mul_f32_e32 v1, v120, v1
	v_mul_f32_e32 v3, v121, v3
	v_cvt_pk_bf16_f32 v125, v1, v3
	s_waitcnt vmcnt(6)
	v_lshlrev_b32_e32 v1, 16, v146
	v_and_b32_e32 v3, 0xffff0000, v146
	v_mul_f32_e32 v1, v114, v1
	v_mul_f32_e32 v3, v115, v3
	global_store_dwordx4 v[192:193], v[122:125], off offset:256
	v_cvt_pk_bf16_f32 v114, v1, v3
	v_lshlrev_b32_e32 v1, 16, v147
	v_and_b32_e32 v3, 0xffff0000, v147
	v_mul_f32_e32 v1, v116, v1
	v_mul_f32_e32 v3, v117, v3
	v_cvt_pk_bf16_f32 v115, v1, v3
	v_lshlrev_b32_e32 v1, 16, v148
	v_and_b32_e32 v3, 0xffff0000, v148
	v_mul_f32_e32 v1, v110, v1
	v_mul_f32_e32 v3, v111, v3
	v_cvt_pk_bf16_f32 v116, v1, v3
	v_lshlrev_b32_e32 v1, 16, v149
	v_and_b32_e32 v3, 0xffff0000, v149
	v_mul_f32_e32 v1, v112, v1
	v_mul_f32_e32 v3, v113, v3
	v_cvt_pk_bf16_f32 v117, v1, v3
	v_lshl_add_u64 v[110:111], s[4:5], 0, v[118:119]
	s_waitcnt vmcnt(6)
	v_lshlrev_b32_e32 v1, 16, v150
	v_and_b32_e32 v3, 0xffff0000, v150
	v_lshl_add_u64 v[110:111], v[110:111], 0, v[4:5]
	v_mul_f32_e32 v1, v106, v1
	v_mul_f32_e32 v3, v107, v3
	global_store_dwordx4 v[110:111], v[114:117], off
	v_cvt_pk_bf16_f32 v106, v1, v3
	v_lshlrev_b32_e32 v1, 16, v151
	v_and_b32_e32 v3, 0xffff0000, v151
	v_mul_f32_e32 v1, v108, v1
	v_mul_f32_e32 v3, v109, v3
	v_cvt_pk_bf16_f32 v107, v1, v3
	v_lshlrev_b32_e32 v1, 16, v152
	v_and_b32_e32 v3, 0xffff0000, v152
	v_mul_f32_e32 v1, v102, v1
	v_mul_f32_e32 v3, v103, v3
	v_cvt_pk_bf16_f32 v108, v1, v3
	v_lshlrev_b32_e32 v1, 16, v153
	v_and_b32_e32 v3, 0xffff0000, v153
	v_mul_f32_e32 v1, v104, v1
	v_mul_f32_e32 v3, v105, v3
	v_cvt_pk_bf16_f32 v109, v1, v3
	s_waitcnt vmcnt(6)
	v_lshlrev_b32_e32 v1, 16, v154
	v_and_b32_e32 v3, 0xffff0000, v154
	v_mul_f32_e32 v1, v98, v1
	v_mul_f32_e32 v3, v99, v3
	global_store_dwordx4 v[110:111], v[106:109], off offset:256
	v_cvt_pk_bf16_f32 v98, v1, v3
	v_lshlrev_b32_e32 v1, 16, v155
	v_and_b32_e32 v3, 0xffff0000, v155
	v_mul_f32_e32 v1, v100, v1
	v_mul_f32_e32 v3, v101, v3
	v_cvt_pk_bf16_f32 v99, v1, v3
	v_lshlrev_b32_e32 v1, 16, v156
	v_and_b32_e32 v3, 0xffff0000, v156
	v_mul_f32_e32 v1, v94, v1
	v_mul_f32_e32 v3, v95, v3
	v_cvt_pk_bf16_f32 v100, v1, v3
	v_lshlrev_b32_e32 v1, 16, v157
	v_and_b32_e32 v3, 0xffff0000, v157
	v_lshlrev_b64 v[102:103], 12, v[172:173]
	v_mul_f32_e32 v1, v96, v1
	v_mul_f32_e32 v3, v97, v3
	v_cvt_pk_bf16_f32 v101, v1, v3
	v_lshl_add_u64 v[94:95], s[4:5], 0, v[102:103]
	s_waitcnt vmcnt(6)
	v_lshlrev_b32_e32 v1, 16, v158
	v_and_b32_e32 v3, 0xffff0000, v158
	v_lshl_add_u64 v[94:95], v[94:95], 0, v[4:5]
	v_mul_f32_e32 v1, v90, v1
	v_mul_f32_e32 v3, v91, v3
	global_store_dwordx4 v[94:95], v[98:101], off
	v_cvt_pk_bf16_f32 v90, v1, v3
	v_lshlrev_b32_e32 v1, 16, v159
	v_and_b32_e32 v3, 0xffff0000, v159
	v_mul_f32_e32 v1, v92, v1
	v_mul_f32_e32 v3, v93, v3
	v_cvt_pk_bf16_f32 v91, v1, v3
	v_lshlrev_b32_e32 v1, 16, v160
	v_and_b32_e32 v3, 0xffff0000, v160
	v_mul_f32_e32 v1, v86, v1
	v_mul_f32_e32 v3, v87, v3
	v_cvt_pk_bf16_f32 v92, v1, v3
	v_lshlrev_b32_e32 v1, 16, v161
	v_and_b32_e32 v3, 0xffff0000, v161
	v_mul_f32_e32 v1, v88, v1
	v_mul_f32_e32 v3, v89, v3
	v_cvt_pk_bf16_f32 v93, v1, v3
	s_waitcnt vmcnt(6)
	v_lshlrev_b32_e32 v1, 16, v162
	v_and_b32_e32 v3, 0xffff0000, v162
	v_mul_f32_e32 v1, v82, v1
	v_mul_f32_e32 v3, v83, v3
	global_store_dwordx4 v[94:95], v[90:93], off offset:256
	v_cvt_pk_bf16_f32 v82, v1, v3
	v_lshlrev_b32_e32 v1, 16, v163
	v_and_b32_e32 v3, 0xffff0000, v163
	v_mul_f32_e32 v1, v84, v1
	v_mul_f32_e32 v3, v85, v3
	v_cvt_pk_bf16_f32 v83, v1, v3
	v_lshlrev_b32_e32 v1, 16, v164
	v_and_b32_e32 v3, 0xffff0000, v164
	v_mul_f32_e32 v1, v78, v1
	v_mul_f32_e32 v3, v79, v3
	v_cvt_pk_bf16_f32 v84, v1, v3
	v_lshlrev_b32_e32 v1, 16, v165
	v_and_b32_e32 v3, 0xffff0000, v165
	v_lshlrev_b64 v[86:87], 12, v[190:191]
	v_mul_f32_e32 v1, v80, v1
	v_mul_f32_e32 v3, v81, v3
	v_cvt_pk_bf16_f32 v85, v1, v3
	v_lshl_add_u64 v[78:79], s[4:5], 0, v[86:87]
	s_waitcnt vmcnt(6)
	v_lshlrev_b32_e32 v1, 16, v166
	v_and_b32_e32 v3, 0xffff0000, v166
	v_lshl_add_u64 v[78:79], v[78:79], 0, v[4:5]
	v_mul_f32_e32 v1, v74, v1
	v_mul_f32_e32 v3, v75, v3
	global_store_dwordx4 v[78:79], v[82:85], off
	v_cvt_pk_bf16_f32 v74, v1, v3
	v_lshlrev_b32_e32 v1, 16, v167
	v_and_b32_e32 v3, 0xffff0000, v167
	v_mul_f32_e32 v1, v76, v1
	v_mul_f32_e32 v3, v77, v3
	v_cvt_pk_bf16_f32 v75, v1, v3
	v_lshlrev_b32_e32 v1, 16, v168
	v_and_b32_e32 v3, 0xffff0000, v168
	v_add_u32_e32 v102, 0x80, v134
	v_mul_f32_e32 v1, v70, v1
	v_mul_f32_e32 v3, v71, v3
	v_mad_i64_i32 v[70:71], s[36:37], v102, s57, v[136:137]
	v_lshl_add_u64 v[80:81], v[70:71], 0, v[4:5]
	v_add_co_u32_e32 v70, vcc, s47, v80
	v_cvt_pk_bf16_f32 v76, v1, v3
	v_lshlrev_b32_e32 v1, 16, v169
	v_and_b32_e32 v3, 0xffff0000, v169
	v_addc_co_u32_e32 v71, vcc, 0, v81, vcc
	v_mul_f32_e32 v1, v72, v1
	v_mul_f32_e32 v3, v73, v3
	v_cvt_pk_bf16_f32 v77, v1, v3
	global_load_dwordx4 v[70:73], v[70:71], off
	v_add_u32_e32 v104, 0x90, v134
	global_store_dwordx4 v[78:79], v[74:77], off offset:256
	v_mad_i64_i32 v[78:79], s[36:37], v104, s57, v[136:137]
	s_nop 0
	v_lshl_add_u64 v[74:75], v[80:81], 0, s[12:13]
	global_load_dwordx4 v[74:77], v[74:75], off offset:256
	v_lshl_add_u64 v[82:83], v[78:79], 0, v[4:5]
	v_add_co_u32_e32 v78, vcc, s47, v82
	v_add_u32_e32 v106, 0xa0, v134
	s_nop 0
	v_addc_co_u32_e32 v79, vcc, 0, v83, vcc
	global_load_dwordx4 v[78:81], v[78:79], off
	v_lshl_add_u64 v[82:83], v[82:83], 0, s[12:13]
	global_load_dwordx4 v[82:85], v[82:83], off offset:256
	v_mad_i64_i32 v[86:87], s[36:37], v106, s57, v[136:137]
	v_lshl_add_u64 v[86:87], v[86:87], 0, v[4:5]
	v_lshl_add_u64 v[90:91], v[86:87], 0, s[12:13]
	v_add_co_u32_e32 v86, vcc, s47, v86
	v_add_u32_e32 v108, 0xb0, v134
	s_nop 0
	v_addc_co_u32_e32 v87, vcc, 0, v87, vcc
	global_load_dwordx4 v[86:89], v[86:87], off
	s_nop 0
	global_load_dwordx4 v[90:93], v[90:91], off offset:256
	v_mad_i64_i32 v[94:95], s[36:37], v108, s57, v[136:137]
	v_lshl_add_u64 v[94:95], v[94:95], 0, v[4:5]
	v_lshl_add_u64 v[98:99], v[94:95], 0, s[12:13]
	v_add_co_u32_e32 v94, vcc, s47, v94
	v_ashrrev_i32_e32 v103, 31, v102
	s_nop 0
	v_addc_co_u32_e32 v95, vcc, 0, v95, vcc
	global_load_dwordx4 v[94:97], v[94:95], off
	s_nop 0
	global_load_dwordx4 v[98:101], v[98:99], off offset:256
	v_lshlrev_b64 v[102:103], 12, v[102:103]
	v_ashrrev_i32_e32 v105, 31, v104
	v_ashrrev_i32_e32 v107, 31, v106
	v_ashrrev_i32_e32 v109, 31, v108
	s_andn2_b64 vcc, exec, s[2:3]
	s_mov_b64 s[2:3], -1
	s_waitcnt vmcnt(8)
	v_lshlrev_b32_e32 v1, 16, v70
	v_and_b32_e32 v3, 0xffff0000, v70
	v_mul_f32_e32 v1, v66, v1
	v_mul_f32_e32 v3, v67, v3
	v_cvt_pk_bf16_f32 v66, v1, v3
	v_lshlrev_b32_e32 v1, 16, v71
	v_and_b32_e32 v3, 0xffff0000, v71
	v_mul_f32_e32 v1, v68, v1
	v_mul_f32_e32 v3, v69, v3
	v_cvt_pk_bf16_f32 v67, v1, v3
	v_lshlrev_b32_e32 v1, 16, v72
	v_and_b32_e32 v3, 0xffff0000, v72
	v_mul_f32_e32 v1, v62, v1
	v_mul_f32_e32 v3, v63, v3
	v_cvt_pk_bf16_f32 v68, v1, v3
	v_lshlrev_b32_e32 v1, 16, v73
	v_and_b32_e32 v3, 0xffff0000, v73
	v_mul_f32_e32 v1, v64, v1
	v_mul_f32_e32 v3, v65, v3
	v_cvt_pk_bf16_f32 v69, v1, v3
	v_lshl_add_u64 v[62:63], s[4:5], 0, v[102:103]
	s_waitcnt vmcnt(6)
	v_lshlrev_b32_e32 v1, 16, v74
	v_and_b32_e32 v3, 0xffff0000, v74
	v_lshl_add_u64 v[62:63], v[62:63], 0, v[4:5]
	v_mul_f32_e32 v1, v58, v1
	v_mul_f32_e32 v3, v59, v3
	global_store_dwordx4 v[62:63], v[66:69], off
	v_cvt_pk_bf16_f32 v58, v1, v3
	v_lshlrev_b32_e32 v1, 16, v75
	v_and_b32_e32 v3, 0xffff0000, v75
	v_mul_f32_e32 v1, v60, v1
	v_mul_f32_e32 v3, v61, v3
	v_cvt_pk_bf16_f32 v59, v1, v3
	v_lshlrev_b32_e32 v1, 16, v76
	v_and_b32_e32 v3, 0xffff0000, v76
	v_mul_f32_e32 v1, v54, v1
	v_mul_f32_e32 v3, v55, v3
	v_cvt_pk_bf16_f32 v60, v1, v3
	v_lshlrev_b32_e32 v1, 16, v77
	v_and_b32_e32 v3, 0xffff0000, v77
	v_mul_f32_e32 v1, v56, v1
	v_mul_f32_e32 v3, v57, v3
	v_cvt_pk_bf16_f32 v61, v1, v3
	s_waitcnt vmcnt(6)
	v_lshlrev_b32_e32 v1, 16, v78
	v_and_b32_e32 v3, 0xffff0000, v78
	v_mul_f32_e32 v1, v50, v1
	v_mul_f32_e32 v3, v51, v3
	global_store_dwordx4 v[62:63], v[58:61], off offset:256
	v_cvt_pk_bf16_f32 v50, v1, v3
	v_lshlrev_b32_e32 v1, 16, v79
	v_and_b32_e32 v3, 0xffff0000, v79
	v_mul_f32_e32 v1, v52, v1
	v_mul_f32_e32 v3, v53, v3
	v_cvt_pk_bf16_f32 v51, v1, v3
	v_lshlrev_b32_e32 v1, 16, v80
	v_and_b32_e32 v3, 0xffff0000, v80
	v_mul_f32_e32 v1, v46, v1
	v_mul_f32_e32 v3, v47, v3
	v_cvt_pk_bf16_f32 v52, v1, v3
	v_lshlrev_b32_e32 v1, 16, v81
	v_and_b32_e32 v3, 0xffff0000, v81
	v_lshlrev_b64 v[54:55], 12, v[104:105]
	v_mul_f32_e32 v1, v48, v1
	v_mul_f32_e32 v3, v49, v3
	v_cvt_pk_bf16_f32 v53, v1, v3
	v_lshl_add_u64 v[46:47], s[4:5], 0, v[54:55]
	s_waitcnt vmcnt(6)
	v_lshlrev_b32_e32 v1, 16, v82
	v_and_b32_e32 v3, 0xffff0000, v82
	v_lshl_add_u64 v[46:47], v[46:47], 0, v[4:5]
	v_mul_f32_e32 v1, v42, v1
	v_mul_f32_e32 v3, v43, v3
	global_store_dwordx4 v[46:47], v[50:53], off
	v_cvt_pk_bf16_f32 v42, v1, v3
	v_lshlrev_b32_e32 v1, 16, v83
	v_and_b32_e32 v3, 0xffff0000, v83
	v_mul_f32_e32 v1, v44, v1
	v_mul_f32_e32 v3, v45, v3
	v_cvt_pk_bf16_f32 v43, v1, v3
	v_lshlrev_b32_e32 v1, 16, v84
	v_and_b32_e32 v3, 0xffff0000, v84
	v_mul_f32_e32 v1, v38, v1
	v_mul_f32_e32 v3, v39, v3
	v_cvt_pk_bf16_f32 v44, v1, v3
	v_lshlrev_b32_e32 v1, 16, v85
	v_and_b32_e32 v3, 0xffff0000, v85
	v_mul_f32_e32 v1, v40, v1
	v_mul_f32_e32 v3, v41, v3
	v_cvt_pk_bf16_f32 v45, v1, v3
	s_waitcnt vmcnt(6)
	v_lshlrev_b32_e32 v1, 16, v86
	v_and_b32_e32 v3, 0xffff0000, v86
	v_mul_f32_e32 v1, v34, v1
	v_mul_f32_e32 v3, v35, v3
	global_store_dwordx4 v[46:47], v[42:45], off offset:256
	v_cvt_pk_bf16_f32 v34, v1, v3
	v_lshlrev_b32_e32 v1, 16, v87
	v_and_b32_e32 v3, 0xffff0000, v87
	v_mul_f32_e32 v1, v36, v1
	v_mul_f32_e32 v3, v37, v3
	v_cvt_pk_bf16_f32 v35, v1, v3
	v_lshlrev_b32_e32 v1, 16, v88
	v_and_b32_e32 v3, 0xffff0000, v88
	v_mul_f32_e32 v1, v30, v1
	v_mul_f32_e32 v3, v31, v3
	v_cvt_pk_bf16_f32 v36, v1, v3
	v_lshlrev_b32_e32 v1, 16, v89
	v_and_b32_e32 v3, 0xffff0000, v89
	v_lshlrev_b64 v[38:39], 12, v[106:107]
	v_mul_f32_e32 v1, v32, v1
	v_mul_f32_e32 v3, v33, v3
	v_cvt_pk_bf16_f32 v37, v1, v3
	v_lshl_add_u64 v[30:31], s[4:5], 0, v[38:39]
	s_waitcnt vmcnt(6)
	v_lshlrev_b32_e32 v1, 16, v90
	v_and_b32_e32 v3, 0xffff0000, v90
	v_lshl_add_u64 v[30:31], v[30:31], 0, v[4:5]
	v_mul_f32_e32 v1, v26, v1
	v_mul_f32_e32 v3, v27, v3
	global_store_dwordx4 v[30:31], v[34:37], off
	v_cvt_pk_bf16_f32 v26, v1, v3
	v_lshlrev_b32_e32 v1, 16, v91
	v_and_b32_e32 v3, 0xffff0000, v91
	v_mul_f32_e32 v1, v28, v1
	v_mul_f32_e32 v3, v29, v3
	v_cvt_pk_bf16_f32 v27, v1, v3
	v_lshlrev_b32_e32 v1, 16, v92
	v_and_b32_e32 v3, 0xffff0000, v92
	v_mul_f32_e32 v1, v22, v1
	v_mul_f32_e32 v3, v23, v3
	v_cvt_pk_bf16_f32 v28, v1, v3
	v_lshlrev_b32_e32 v1, 16, v93
	v_and_b32_e32 v3, 0xffff0000, v93
	v_mul_f32_e32 v1, v24, v1
	v_mul_f32_e32 v3, v25, v3
	v_cvt_pk_bf16_f32 v29, v1, v3
	s_waitcnt vmcnt(6)
	v_lshlrev_b32_e32 v1, 16, v94
	v_and_b32_e32 v3, 0xffff0000, v94
	v_mul_f32_e32 v1, v18, v1
	v_mul_f32_e32 v3, v19, v3
	global_store_dwordx4 v[30:31], v[26:29], off offset:256
	v_cvt_pk_bf16_f32 v18, v1, v3
	v_lshlrev_b32_e32 v1, 16, v95
	v_and_b32_e32 v3, 0xffff0000, v95
	v_mul_f32_e32 v1, v20, v1
	v_mul_f32_e32 v3, v21, v3
	v_cvt_pk_bf16_f32 v19, v1, v3
	v_lshlrev_b32_e32 v1, 16, v96
	v_and_b32_e32 v3, 0xffff0000, v96
	v_mul_f32_e32 v1, v14, v1
	v_mul_f32_e32 v3, v15, v3
	v_cvt_pk_bf16_f32 v20, v1, v3
	v_lshlrev_b32_e32 v1, 16, v97
	v_and_b32_e32 v3, 0xffff0000, v97
	v_lshlrev_b64 v[22:23], 12, v[108:109]
	v_mul_f32_e32 v1, v16, v1
	v_mul_f32_e32 v3, v17, v3
	v_cvt_pk_bf16_f32 v21, v1, v3
	v_lshl_add_u64 v[14:15], s[4:5], 0, v[22:23]
	s_waitcnt vmcnt(6)
	v_lshlrev_b32_e32 v1, 16, v98
	v_and_b32_e32 v3, 0xffff0000, v98
	v_lshl_add_u64 v[14:15], v[14:15], 0, v[4:5]
	v_mul_f32_e32 v1, v10, v1
	v_mul_f32_e32 v3, v11, v3
	global_store_dwordx4 v[14:15], v[18:21], off
	v_cvt_pk_bf16_f32 v4, v1, v3
	v_lshlrev_b32_e32 v1, 16, v99
	v_and_b32_e32 v3, 0xffff0000, v99
	v_mul_f32_e32 v1, v12, v1
	v_mul_f32_e32 v3, v13, v3
	v_cvt_pk_bf16_f32 v5, v1, v3
	v_lshlrev_b32_e32 v1, 16, v100
	v_and_b32_e32 v3, 0xffff0000, v100
	v_mul_f32_e32 v1, v6, v1
	v_mul_f32_e32 v3, v7, v3
	v_cvt_pk_bf16_f32 v6, v1, v3
	v_lshlrev_b32_e32 v1, 16, v101
	v_and_b32_e32 v3, 0xffff0000, v101
	v_mul_f32_e32 v1, v8, v1
	v_mul_f32_e32 v3, v9, v3
	v_cvt_pk_bf16_f32 v7, v1, v3
	global_store_dwordx4 v[14:15], v[4:7], off offset:256
	s_cbranch_vccnz .LBB0_1317
	s_andn2_b64 vcc, exec, s[0:1]
	s_cbranch_vccnz .LBB0_1316
	s_barrier
	s_branch .LBB0_1316

.LBB0_1411:
	s_lshl_b32 s37, s44, 8
	s_add_i32 s37, s37, s59
	v_or_b32_e32 v166, s37, v180
	v_lshl_or_b32 v164, s65, 8, v182
	v_ashrrev_i32_e32 v167, 31, v166
	v_ashrrev_i32_e32 v165, 31, v164
	v_lshlrev_b64 v[130:131], 11, v[166:167]
	v_lshl_add_u64 v[130:131], v[130:131], 0, v[164:165]
	v_lshlrev_b64 v[204:205], 1, v[130:131]
	v_lshl_add_u64 v[130:131], s[12:13], 0, v[204:205]
	v_or_b32_e32 v206, 0x100, v204
	v_mov_b32_e32 v207, v205
	global_load_dwordx4 v[188:191], v[130:131], off
	v_lshl_add_u64 v[130:131], s[12:13], 0, v[206:207]
	global_load_dwordx4 v[192:195], v[130:131], off
	v_or_b32_e32 v130, 16, v166
	v_or_b32_e32 v132, 32, v166
	v_or_b32_e32 v134, 48, v166
	v_ashrrev_i32_e32 v131, 31, v130
	v_ashrrev_i32_e32 v133, 31, v132
	v_ashrrev_i32_e32 v135, 31, v134
	v_lshlrev_b64 v[130:131], 11, v[130:131]
	v_lshlrev_b64 v[132:133], 11, v[132:133]
	v_lshlrev_b64 v[134:135], 11, v[134:135]
	v_lshl_add_u64 v[130:131], v[130:131], 0, v[164:165]
	v_lshl_add_u64 v[132:133], v[132:133], 0, v[164:165]
	v_lshl_add_u64 v[134:135], v[134:135], 0, v[164:165]
	v_lshlrev_b64 v[178:179], 1, v[130:131]
	v_lshlrev_b64 v[174:175], 1, v[132:133]
	v_lshlrev_b64 v[168:169], 1, v[134:135]
	v_or_b32_e32 v176, 0x100, v178
	v_mov_b32_e32 v177, v179
	v_or_b32_e32 v172, 0x100, v174
	v_mov_b32_e32 v173, v175
	v_lshl_add_u64 v[130:131], s[12:13], 0, v[178:179]
	v_lshl_add_u64 v[132:133], s[12:13], 0, v[174:175]
	v_lshl_add_u64 v[134:135], s[12:13], 0, v[168:169]
	v_or_b32_e32 v170, 0x100, v168
	v_mov_b32_e32 v171, v169
	v_lshl_add_u64 v[136:137], s[12:13], 0, v[176:177]
	v_lshl_add_u64 v[138:139], s[12:13], 0, v[172:173]
	v_lshl_add_u64 v[208:209], s[12:13], 0, v[170:171]
	global_load_dwordx4 v[196:199], v[130:131], off
	global_load_dwordx4 v[200:203], v[136:137], off
	global_load_dwordx4 v[142:145], v[132:133], off
	s_nop 0
	global_load_dwordx4 v[138:141], v[138:139], off
	s_nop 0
	global_load_dwordx4 v[134:137], v[134:135], off
	s_nop 0
	global_load_dwordx4 v[130:133], v[208:209], off
	v_or_b32_e32 v162, s37, v252
	s_waitcnt vmcnt(7)
	v_lshlrev_b32_e32 v208, 16, v188
	v_and_b32_e32 v209, 0xffff0000, v188
	v_lshlrev_b32_e32 v188, 16, v189
	v_and_b32_e32 v189, 0xffff0000, v189
	v_lshlrev_b32_e32 v210, 16, v190
	v_and_b32_e32 v211, 0xffff0000, v190
	v_lshlrev_b32_e32 v190, 16, v191
	v_and_b32_e32 v191, 0xffff0000, v191
	v_pk_add_f32 v[126:127], v[126:127], v[208:209]
	s_waitcnt vmcnt(6)
	v_lshlrev_b32_e32 v208, 16, v192
	v_and_b32_e32 v209, 0xffff0000, v192
	v_lshlrev_b32_e32 v192, 16, v193
	v_and_b32_e32 v193, 0xffff0000, v193
	v_pk_add_f32 v[128:129], v[128:129], v[188:189]
	v_pk_add_f32 v[188:189], v[124:125], v[190:191]
	v_pk_add_f32 v[190:191], v[122:123], v[210:211]
	v_lshlrev_b32_e32 v210, 16, v194
	v_and_b32_e32 v211, 0xffff0000, v194
	v_lshlrev_b32_e32 v194, 16, v195
	v_and_b32_e32 v195, 0xffff0000, v195
	v_pk_add_f32 v[120:121], v[120:121], v[192:193]
	v_pk_add_f32 v[118:119], v[118:119], v[208:209]
	v_pk_add_f32 v[192:193], v[116:117], v[194:195]
	v_pk_add_f32 v[194:195], v[114:115], v[210:211]
	v_mul_f32_e32 v114, v119, v119
	v_mul_f32_e32 v115, v120, v120
	v_fmac_f32_e32 v114, v118, v118
	v_fmac_f32_e32 v115, v121, v121
	v_cvt_pk_bf16_f32 v122, v126, v127
	v_cvt_pk_bf16_f32 v123, v128, v129
	v_mul_f32_e32 v1, v127, v127
	v_mul_f32_e32 v127, v128, v128
	v_mul_f32_e32 v128, v190, v190
	v_mul_f32_e32 v163, v188, v188
	v_mul_f32_e32 v116, v194, v194
	v_add_f32_e32 v114, v114, v115
	v_mul_f32_e32 v115, v192, v192
	v_fmac_f32_e32 v1, v126, v126
	v_fmac_f32_e32 v127, v129, v129
	v_fmac_f32_e32 v128, v191, v191
	v_fmac_f32_e32 v163, v189, v189
	v_fmac_f32_e32 v116, v195, v195
	v_fmac_f32_e32 v115, v193, v193
	v_add_f32_e32 v1, v1, v127
	v_add_f32_e32 v117, v163, v128
	v_add_f32_e32 v115, v115, v116
	v_add_f32_e32 v1, v117, v1
	v_add_f32_e32 v114, v115, v114
	v_and_b32_e32 v115, 64, v186
	v_add_f32_e32 v1, v1, v114
	v_xor_b32_e32 v114, 16, v186
	v_add_u32_e32 v115, 64, v115
	v_cmp_lt_i32_e32 vcc, v114, v115
	v_lshl_add_u64 v[116:117], s[14:15], 0, v[204:205]
	v_cvt_pk_bf16_f32 v124, v190, v191
	v_cvt_pk_bf16_f32 v125, v188, v189
	global_store_dwordx4 v[116:117], v[122:125], off
	v_cndmask_b32_e32 v114, v186, v114, vcc
	v_lshlrev_b32_e32 v114, 2, v114
	ds_bpermute_b32 v126, v114, v1
	v_cvt_pk_bf16_f32 v116, v118, v119
	v_xor_b32_e32 v118, 32, v186
	v_cmp_lt_i32_e32 vcc, v118, v115
	v_cvt_pk_bf16_f32 v117, v120, v121
	s_waitcnt lgkmcnt(0)
	v_add_f32_e32 v1, v1, v126
	v_lshl_add_u64 v[120:121], s[14:15], 0, v[206:207]
	v_cndmask_b32_e32 v115, v186, v118, vcc
	v_lshlrev_b32_e32 v115, 2, v115
	ds_bpermute_b32 v122, v115, v1
	v_cvt_pk_bf16_f32 v118, v194, v195
	v_cvt_pk_bf16_f32 v119, v192, v193
	global_store_dwordx4 v[120:121], v[116:119], off
	s_waitcnt vmcnt(7)
	v_lshlrev_b32_e32 v120, 16, v198
	v_and_b32_e32 v121, 0xffff0000, v198
	v_lshlrev_b32_e32 v116, 16, v196
	v_and_b32_e32 v117, 0xffff0000, v196
	v_lshlrev_b32_e32 v118, 16, v197
	v_and_b32_e32 v119, 0xffff0000, v197
	v_pk_add_f32 v[110:111], v[110:111], v[116:117]
	v_pk_add_f32 v[112:113], v[112:113], v[118:119]
	v_pk_add_f32 v[118:119], v[106:107], v[120:121]
	v_cvt_pk_bf16_f32 v106, v110, v111
	v_mul_f32_e32 v111, v111, v111
	s_waitcnt lgkmcnt(0)
	v_add_f32_e32 v1, v1, v122
	v_lshlrev_b32_e32 v122, 16, v199
	v_and_b32_e32 v123, 0xffff0000, v199
	v_fmac_f32_e32 v111, v110, v110
	v_mul_f32_e32 v110, v112, v112
	v_pk_add_f32 v[116:117], v[108:109], v[122:123]
	v_fmac_f32_e32 v110, v113, v113
	v_cvt_pk_bf16_f32 v107, v112, v113
	v_add_f32_e32 v110, v111, v110
	v_mul_f32_e32 v111, v118, v118
	v_mul_f32_e32 v112, v116, v116
	v_fmac_f32_e32 v111, v119, v119
	v_fmac_f32_e32 v112, v117, v117
	v_add_f32_e32 v111, v112, v111
	v_add_f32_e32 v120, v111, v110
	s_waitcnt vmcnt(6)
	v_lshlrev_b32_e32 v110, 16, v200
	v_and_b32_e32 v111, 0xffff0000, v200
	v_lshlrev_b32_e32 v112, 16, v201
	v_and_b32_e32 v113, 0xffff0000, v201
	v_cvt_pk_bf16_f32 v108, v118, v119
	v_cvt_pk_bf16_f32 v109, v116, v117
	v_lshlrev_b32_e32 v116, 16, v202
	v_and_b32_e32 v117, 0xffff0000, v202
	v_lshlrev_b32_e32 v118, 16, v203
	v_and_b32_e32 v119, 0xffff0000, v203
	v_pk_add_f32 v[104:105], v[104:105], v[112:113]
	v_pk_add_f32 v[102:103], v[102:103], v[110:111]
	v_pk_add_f32 v[110:111], v[100:101], v[118:119]
	v_pk_add_f32 v[100:101], v[98:99], v[116:117]
	v_mul_f32_e32 v98, v103, v103
	v_mul_f32_e32 v99, v104, v104
	v_fmac_f32_e32 v98, v102, v102
	v_fmac_f32_e32 v99, v105, v105
	v_add_f32_e32 v98, v98, v99
	v_mul_f32_e32 v99, v100, v100
	v_mul_f32_e32 v112, v110, v110
	v_fmac_f32_e32 v99, v101, v101
	v_fmac_f32_e32 v112, v111, v111
	v_add_f32_e32 v99, v112, v99
	v_add_f32_e32 v98, v99, v98
	v_add_f32_e32 v112, v120, v98
	ds_bpermute_b32 v113, v114, v112
	v_lshl_add_u64 v[98:99], s[14:15], 0, v[178:179]
	global_store_dwordx4 v[98:99], v[106:109], off
	v_cvt_pk_bf16_f32 v98, v102, v103
	v_cvt_pk_bf16_f32 v99, v104, v105
	s_waitcnt lgkmcnt(0)
	v_add_f32_e32 v104, v112, v113
	ds_bpermute_b32 v105, v115, v104
	v_lshl_add_u64 v[102:103], s[14:15], 0, v[176:177]
	v_cndmask_b32_e64 v1, 0, v1, s[2:3]
	v_cvt_pk_bf16_f32 v100, v100, v101
	v_cvt_pk_bf16_f32 v101, v110, v111
	global_store_dwordx4 v[102:103], v[98:101], off
	s_waitcnt vmcnt(7)
	v_lshlrev_b32_e32 v102, 16, v144
	v_and_b32_e32 v103, 0xffff0000, v144
	s_waitcnt lgkmcnt(0)
	v_add_f32_e32 v98, v104, v105
	v_cndmask_b32_e64 v1, v1, v98, s[4:5]
	v_lshlrev_b32_e32 v98, 16, v142
	v_and_b32_e32 v99, 0xffff0000, v142
	v_lshlrev_b32_e32 v100, 16, v143
	v_and_b32_e32 v101, 0xffff0000, v143
	v_pk_add_f32 v[94:95], v[94:95], v[98:99]
	v_pk_add_f32 v[96:97], v[96:97], v[100:101]
	v_pk_add_f32 v[100:101], v[90:91], v[102:103]
	v_cvt_pk_bf16_f32 v90, v94, v95
	v_mul_f32_e32 v95, v95, v95
	v_lshlrev_b32_e32 v104, 16, v145
	v_and_b32_e32 v105, 0xffff0000, v145
	v_fmac_f32_e32 v95, v94, v94
	v_mul_f32_e32 v94, v96, v96
	v_pk_add_f32 v[98:99], v[92:93], v[104:105]
	v_fmac_f32_e32 v94, v97, v97
	v_cvt_pk_bf16_f32 v91, v96, v97
	v_add_f32_e32 v94, v95, v94
	v_mul_f32_e32 v95, v100, v100
	v_mul_f32_e32 v96, v98, v98
	v_fmac_f32_e32 v95, v101, v101
	v_fmac_f32_e32 v96, v99, v99
	v_add_f32_e32 v95, v96, v95
	v_add_f32_e32 v102, v95, v94
	s_waitcnt vmcnt(6)
	v_lshlrev_b32_e32 v94, 16, v138
	v_and_b32_e32 v95, 0xffff0000, v138
	v_lshlrev_b32_e32 v96, 16, v139
	v_and_b32_e32 v97, 0xffff0000, v139
	v_cvt_pk_bf16_f32 v92, v100, v101
	v_cvt_pk_bf16_f32 v93, v98, v99
	v_lshlrev_b32_e32 v98, 16, v140
	v_and_b32_e32 v99, 0xffff0000, v140
	v_lshlrev_b32_e32 v100, 16, v141
	v_and_b32_e32 v101, 0xffff0000, v141
	v_pk_add_f32 v[88:89], v[88:89], v[96:97]
	v_pk_add_f32 v[86:87], v[86:87], v[94:95]
	v_pk_add_f32 v[94:95], v[84:85], v[100:101]
	v_pk_add_f32 v[84:85], v[82:83], v[98:99]
	v_mul_f32_e32 v82, v87, v87
	v_mul_f32_e32 v83, v88, v88
	v_fmac_f32_e32 v82, v86, v86
	v_fmac_f32_e32 v83, v89, v89
	v_add_f32_e32 v82, v82, v83
	v_mul_f32_e32 v83, v84, v84
	v_mul_f32_e32 v96, v94, v94
	v_fmac_f32_e32 v83, v85, v85
	v_fmac_f32_e32 v96, v95, v95
	v_add_f32_e32 v83, v96, v83
	v_add_f32_e32 v82, v83, v82
	v_add_f32_e32 v96, v102, v82
	ds_bpermute_b32 v97, v114, v96
	v_lshl_add_u64 v[82:83], s[14:15], 0, v[174:175]
	global_store_dwordx4 v[82:83], v[90:93], off
	v_cvt_pk_bf16_f32 v82, v86, v87
	v_cvt_pk_bf16_f32 v83, v88, v89
	s_waitcnt lgkmcnt(0)
	v_add_f32_e32 v88, v96, v97
	ds_bpermute_b32 v89, v115, v88
	v_lshl_add_u64 v[86:87], s[14:15], 0, v[172:173]
	v_cvt_pk_bf16_f32 v84, v84, v85
	v_cvt_pk_bf16_f32 v85, v94, v95
	global_store_dwordx4 v[86:87], v[82:85], off
	s_waitcnt vmcnt(7)
	v_lshlrev_b32_e32 v86, 16, v136
	v_and_b32_e32 v87, 0xffff0000, v136
	s_waitcnt lgkmcnt(0)
	v_add_f32_e32 v82, v88, v89
	v_cndmask_b32_e64 v1, v1, v82, s[6:7]
	v_lshlrev_b32_e32 v82, 16, v134
	v_and_b32_e32 v83, 0xffff0000, v134
	v_lshlrev_b32_e32 v84, 16, v135
	v_and_b32_e32 v85, 0xffff0000, v135
	v_pk_add_f32 v[78:79], v[78:79], v[82:83]
	v_pk_add_f32 v[80:81], v[80:81], v[84:85]
	v_pk_add_f32 v[84:85], v[74:75], v[86:87]
	v_cvt_pk_bf16_f32 v74, v78, v79
	v_mul_f32_e32 v79, v79, v79
	v_lshlrev_b32_e32 v88, 16, v137
	v_and_b32_e32 v89, 0xffff0000, v137
	v_fmac_f32_e32 v79, v78, v78
	v_mul_f32_e32 v78, v80, v80
	v_pk_add_f32 v[82:83], v[76:77], v[88:89]
	v_fmac_f32_e32 v78, v81, v81
	v_cvt_pk_bf16_f32 v75, v80, v81
	v_add_f32_e32 v78, v79, v78
	v_mul_f32_e32 v79, v84, v84
	v_mul_f32_e32 v80, v82, v82
	v_fmac_f32_e32 v79, v85, v85
	v_fmac_f32_e32 v80, v83, v83
	v_add_f32_e32 v79, v80, v79
	v_add_f32_e32 v86, v79, v78
	s_waitcnt vmcnt(6)
	v_lshlrev_b32_e32 v78, 16, v130
	v_and_b32_e32 v79, 0xffff0000, v130
	v_lshlrev_b32_e32 v80, 16, v131
	v_and_b32_e32 v81, 0xffff0000, v131
	v_cvt_pk_bf16_f32 v76, v84, v85
	v_cvt_pk_bf16_f32 v77, v82, v83
	v_lshlrev_b32_e32 v82, 16, v132
	v_and_b32_e32 v83, 0xffff0000, v132
	v_lshlrev_b32_e32 v84, 16, v133
	v_and_b32_e32 v85, 0xffff0000, v133
	v_pk_add_f32 v[72:73], v[72:73], v[80:81]
	v_pk_add_f32 v[70:71], v[70:71], v[78:79]
	v_pk_add_f32 v[78:79], v[68:69], v[84:85]
	v_pk_add_f32 v[68:69], v[66:67], v[82:83]
	v_mul_f32_e32 v66, v71, v71
	v_mul_f32_e32 v67, v72, v72
	v_fmac_f32_e32 v66, v70, v70
	v_fmac_f32_e32 v67, v73, v73
	v_add_f32_e32 v66, v66, v67
	v_mul_f32_e32 v67, v68, v68
	v_mul_f32_e32 v80, v78, v78
	v_fmac_f32_e32 v67, v69, v69
	v_fmac_f32_e32 v80, v79, v79
	v_add_f32_e32 v67, v80, v67
	v_add_f32_e32 v66, v67, v66
	v_add_f32_e32 v80, v86, v66
	ds_bpermute_b32 v81, v114, v80
	v_lshl_add_u64 v[66:67], s[14:15], 0, v[168:169]
	global_store_dwordx4 v[66:67], v[74:77], off
	v_cvt_pk_bf16_f32 v66, v70, v71
	v_cvt_pk_bf16_f32 v67, v72, v73
	s_waitcnt lgkmcnt(0)
	v_add_f32_e32 v72, v80, v81
	ds_bpermute_b32 v73, v115, v72
	v_lshl_add_u64 v[70:71], s[14:15], 0, v[170:171]
	v_cvt_pk_bf16_f32 v68, v68, v69
	v_cvt_pk_bf16_f32 v69, v78, v79
	global_store_dwordx4 v[70:71], v[66:69], off
	v_ashrrev_i32_e32 v163, 31, v162
	s_andn2_b64 vcc, exec, s[10:11]
	s_waitcnt lgkmcnt(0)
	v_add_f32_e32 v66, v72, v73
	v_cndmask_b32_e64 v1, v1, v66, s[8:9]
	v_lshl_add_u64 v[66:67], v[162:163], 2, s[16:17]
	global_atomic_add_f32 v[66:67], v1, off
	v_add_u32_e32 v66, 0x80, v166
	v_ashrrev_i32_e32 v67, 31, v66
	v_lshlrev_b64 v[66:67], 11, v[66:67]
	v_lshl_add_u64 v[66:67], v[66:67], 0, v[164:165]
	v_lshlrev_b64 v[110:111], 1, v[66:67]
	v_lshl_add_u64 v[66:67], s[12:13], 0, v[110:111]
	global_load_dwordx4 v[94:97], v[66:67], off
	v_or_b32_e32 v112, 0x100, v110
	v_mov_b32_e32 v113, v111
	v_lshl_add_u64 v[66:67], s[12:13], 0, v[112:113]
	global_load_dwordx4 v[98:101], v[66:67], off
	v_add_u32_e32 v66, 0x90, v166
	v_ashrrev_i32_e32 v67, 31, v66
	v_lshlrev_b64 v[66:67], 11, v[66:67]
	v_lshl_add_u64 v[66:67], v[66:67], 0, v[164:165]
	v_lshlrev_b64 v[92:93], 1, v[66:67]
	v_lshl_add_u64 v[66:67], s[12:13], 0, v[92:93]
	v_or_b32_e32 v90, 0x100, v92
	v_mov_b32_e32 v91, v93
	v_lshl_add_u64 v[68:69], s[12:13], 0, v[90:91]
	global_load_dwordx4 v[102:105], v[66:67], off
	global_load_dwordx4 v[106:109], v[68:69], off
	v_add_u32_e32 v66, 0xa0, v166
	v_ashrrev_i32_e32 v67, 31, v66
	v_lshlrev_b64 v[66:67], 11, v[66:67]
	v_lshl_add_u64 v[66:67], v[66:67], 0, v[164:165]
	v_lshlrev_b64 v[88:89], 1, v[66:67]
	v_lshl_add_u64 v[66:67], s[12:13], 0, v[88:89]
	v_or_b32_e32 v86, 0x100, v88
	v_mov_b32_e32 v87, v89
	v_lshl_add_u64 v[68:69], s[12:13], 0, v[86:87]
	global_load_dwordx4 v[78:81], v[66:67], off
	global_load_dwordx4 v[74:77], v[68:69], off
	v_add_u32_e32 v66, 0xb0, v166
	v_ashrrev_i32_e32 v67, 31, v66
	v_lshlrev_b64 v[66:67], 11, v[66:67]
	v_lshl_add_u64 v[66:67], v[66:67], 0, v[164:165]
	v_lshlrev_b64 v[84:85], 1, v[66:67]
	v_or_b32_e32 v82, 0x100, v84
	v_mov_b32_e32 v83, v85
	v_lshl_add_u64 v[66:67], s[12:13], 0, v[84:85]
	v_lshl_add_u64 v[68:69], s[12:13], 0, v[82:83]
	global_load_dwordx4 v[70:73], v[66:67], off
	s_nop 0
	global_load_dwordx4 v[66:69], v[68:69], off
	s_mov_b64 s[10:11], -1
	s_waitcnt vmcnt(7)
	v_lshlrev_b32_e32 v116, 16, v94
	v_and_b32_e32 v117, 0xffff0000, v94
	v_lshlrev_b32_e32 v94, 16, v95
	v_and_b32_e32 v95, 0xffff0000, v95
	v_pk_add_f32 v[62:63], v[62:63], v[116:117]
	v_lshlrev_b32_e32 v118, 16, v96
	v_and_b32_e32 v119, 0xffff0000, v96
	v_lshlrev_b32_e32 v96, 16, v97
	v_and_b32_e32 v97, 0xffff0000, v97
	v_pk_add_f32 v[64:65], v[64:65], v[94:95]
	v_mul_f32_e32 v1, v63, v63
	v_pk_add_f32 v[94:95], v[60:61], v[96:97]
	v_pk_add_f32 v[96:97], v[58:59], v[118:119]
	v_cvt_pk_bf16_f32 v58, v62, v63
	v_fmac_f32_e32 v1, v62, v62
	v_mul_f32_e32 v62, v64, v64
	v_fmac_f32_e32 v62, v65, v65
	v_add_f32_e32 v1, v1, v62
	v_mul_f32_e32 v62, v96, v96
	v_mul_f32_e32 v63, v94, v94
	v_fmac_f32_e32 v62, v97, v97
	v_fmac_f32_e32 v63, v95, v95
	v_add_f32_e32 v62, v63, v62
	v_cvt_pk_bf16_f32 v59, v64, v65
	v_add_f32_e32 v1, v62, v1
	s_waitcnt vmcnt(6)
	v_lshlrev_b32_e32 v62, 16, v98
	v_and_b32_e32 v63, 0xffff0000, v98
	v_lshlrev_b32_e32 v64, 16, v99
	v_and_b32_e32 v65, 0xffff0000, v99
	v_cvt_pk_bf16_f32 v60, v96, v97
	v_cvt_pk_bf16_f32 v61, v94, v95
	v_lshlrev_b32_e32 v94, 16, v100
	v_and_b32_e32 v95, 0xffff0000, v100
	v_lshlrev_b32_e32 v96, 16, v101
	v_and_b32_e32 v97, 0xffff0000, v101
	v_pk_add_f32 v[56:57], v[56:57], v[64:65]
	v_pk_add_f32 v[54:55], v[54:55], v[62:63]
	v_pk_add_f32 v[62:63], v[52:53], v[96:97]
	v_pk_add_f32 v[52:53], v[50:51], v[94:95]
	v_mul_f32_e32 v50, v55, v55
	v_mul_f32_e32 v51, v56, v56
	v_fmac_f32_e32 v50, v54, v54
	v_fmac_f32_e32 v51, v57, v57
	v_add_f32_e32 v50, v50, v51
	v_mul_f32_e32 v51, v52, v52
	v_mul_f32_e32 v64, v62, v62
	v_fmac_f32_e32 v51, v53, v53
	v_fmac_f32_e32 v64, v63, v63
	v_add_f32_e32 v51, v64, v51
	v_add_f32_e32 v50, v51, v50
	v_add_f32_e32 v1, v1, v50
	ds_bpermute_b32 v64, v114, v1
	v_lshl_add_u64 v[50:51], s[14:15], 0, v[110:111]
	global_store_dwordx4 v[50:51], v[58:61], off
	v_cvt_pk_bf16_f32 v50, v54, v55
	v_cvt_pk_bf16_f32 v51, v56, v57
	s_waitcnt lgkmcnt(0)
	v_add_f32_e32 v1, v1, v64
	ds_bpermute_b32 v56, v115, v1
	v_lshl_add_u64 v[54:55], s[14:15], 0, v[112:113]
	v_cvt_pk_bf16_f32 v52, v52, v53
	v_cvt_pk_bf16_f32 v53, v62, v63
	global_store_dwordx4 v[54:55], v[50:53], off
	s_waitcnt vmcnt(7)
	v_lshlrev_b32_e32 v54, 16, v104
	v_and_b32_e32 v55, 0xffff0000, v104
	v_lshlrev_b32_e32 v50, 16, v102
	v_and_b32_e32 v51, 0xffff0000, v102
	v_lshlrev_b32_e32 v52, 16, v103
	v_and_b32_e32 v53, 0xffff0000, v103
	v_pk_add_f32 v[46:47], v[46:47], v[50:51]
	v_pk_add_f32 v[48:49], v[48:49], v[52:53]
	v_pk_add_f32 v[52:53], v[42:43], v[54:55]
	v_cvt_pk_bf16_f32 v42, v46, v47
	v_mul_f32_e32 v47, v47, v47
	s_waitcnt lgkmcnt(0)
	v_add_f32_e32 v1, v1, v56
	v_lshlrev_b32_e32 v56, 16, v105
	v_and_b32_e32 v57, 0xffff0000, v105
	v_fmac_f32_e32 v47, v46, v46
	v_mul_f32_e32 v46, v48, v48
	v_pk_add_f32 v[50:51], v[44:45], v[56:57]
	v_fmac_f32_e32 v46, v49, v49
	v_cvt_pk_bf16_f32 v43, v48, v49
	v_add_f32_e32 v46, v47, v46
	v_mul_f32_e32 v47, v52, v52
	v_mul_f32_e32 v48, v50, v50
	v_fmac_f32_e32 v47, v53, v53
	v_fmac_f32_e32 v48, v51, v51
	v_add_f32_e32 v47, v48, v47
	v_add_f32_e32 v54, v47, v46
	s_waitcnt vmcnt(6)
	v_lshlrev_b32_e32 v46, 16, v106
	v_and_b32_e32 v47, 0xffff0000, v106
	v_lshlrev_b32_e32 v48, 16, v107
	v_and_b32_e32 v49, 0xffff0000, v107
	v_cvt_pk_bf16_f32 v44, v52, v53
	v_cvt_pk_bf16_f32 v45, v50, v51
	v_lshlrev_b32_e32 v50, 16, v108
	v_and_b32_e32 v51, 0xffff0000, v108
	v_lshlrev_b32_e32 v52, 16, v109
	v_and_b32_e32 v53, 0xffff0000, v109
	v_pk_add_f32 v[40:41], v[40:41], v[48:49]
	v_pk_add_f32 v[38:39], v[38:39], v[46:47]
	v_pk_add_f32 v[46:47], v[36:37], v[52:53]
	v_pk_add_f32 v[36:37], v[34:35], v[50:51]
	v_mul_f32_e32 v34, v39, v39
	v_mul_f32_e32 v35, v40, v40
	v_fmac_f32_e32 v34, v38, v38
	v_fmac_f32_e32 v35, v41, v41
	v_add_f32_e32 v34, v34, v35
	v_mul_f32_e32 v35, v36, v36
	v_mul_f32_e32 v48, v46, v46
	v_fmac_f32_e32 v35, v37, v37
	v_fmac_f32_e32 v48, v47, v47
	v_add_f32_e32 v35, v48, v35
	v_add_f32_e32 v34, v35, v34
	v_add_f32_e32 v48, v54, v34
	ds_bpermute_b32 v49, v114, v48
	v_lshl_add_u64 v[34:35], s[14:15], 0, v[92:93]
	global_store_dwordx4 v[34:35], v[42:45], off
	v_cvt_pk_bf16_f32 v34, v38, v39
	v_cvt_pk_bf16_f32 v35, v40, v41
	s_waitcnt lgkmcnt(0)
	v_add_f32_e32 v40, v48, v49
	ds_bpermute_b32 v41, v115, v40
	v_lshl_add_u64 v[38:39], s[14:15], 0, v[90:91]
	v_cndmask_b32_e64 v1, 0, v1, s[2:3]
	v_cvt_pk_bf16_f32 v36, v36, v37
	v_cvt_pk_bf16_f32 v37, v46, v47
	global_store_dwordx4 v[38:39], v[34:37], off
	s_waitcnt vmcnt(7)
	v_lshlrev_b32_e32 v38, 16, v80
	v_and_b32_e32 v39, 0xffff0000, v80
	s_waitcnt lgkmcnt(0)
	v_add_f32_e32 v34, v40, v41
	v_cndmask_b32_e64 v1, v1, v34, s[4:5]
	v_lshlrev_b32_e32 v34, 16, v78
	v_and_b32_e32 v35, 0xffff0000, v78
	v_lshlrev_b32_e32 v36, 16, v79
	v_and_b32_e32 v37, 0xffff0000, v79
	v_pk_add_f32 v[30:31], v[30:31], v[34:35]
	v_pk_add_f32 v[32:33], v[32:33], v[36:37]
	v_pk_add_f32 v[36:37], v[26:27], v[38:39]
	v_cvt_pk_bf16_f32 v26, v30, v31
	v_mul_f32_e32 v31, v31, v31
	v_lshlrev_b32_e32 v40, 16, v81
	v_and_b32_e32 v41, 0xffff0000, v81
	v_fmac_f32_e32 v31, v30, v30
	v_mul_f32_e32 v30, v32, v32
	v_pk_add_f32 v[34:35], v[28:29], v[40:41]
	v_fmac_f32_e32 v30, v33, v33
	v_cvt_pk_bf16_f32 v27, v32, v33
	v_add_f32_e32 v30, v31, v30
	v_mul_f32_e32 v31, v36, v36
	v_mul_f32_e32 v32, v34, v34
	v_fmac_f32_e32 v31, v37, v37
	v_fmac_f32_e32 v32, v35, v35
	v_add_f32_e32 v31, v32, v31
	v_add_f32_e32 v38, v31, v30
	s_waitcnt vmcnt(6)
	v_lshlrev_b32_e32 v30, 16, v74
	v_and_b32_e32 v31, 0xffff0000, v74
	v_lshlrev_b32_e32 v32, 16, v75
	v_and_b32_e32 v33, 0xffff0000, v75
	v_cvt_pk_bf16_f32 v28, v36, v37
	v_cvt_pk_bf16_f32 v29, v34, v35
	v_lshlrev_b32_e32 v34, 16, v76
	v_and_b32_e32 v35, 0xffff0000, v76
	v_lshlrev_b32_e32 v36, 16, v77
	v_and_b32_e32 v37, 0xffff0000, v77
	v_pk_add_f32 v[24:25], v[24:25], v[32:33]
	v_pk_add_f32 v[22:23], v[22:23], v[30:31]
	v_pk_add_f32 v[30:31], v[20:21], v[36:37]
	v_pk_add_f32 v[20:21], v[18:19], v[34:35]
	v_mul_f32_e32 v18, v23, v23
	v_mul_f32_e32 v19, v24, v24
	v_fmac_f32_e32 v18, v22, v22
	v_fmac_f32_e32 v19, v25, v25
	v_add_f32_e32 v18, v18, v19
	v_mul_f32_e32 v19, v20, v20
	v_mul_f32_e32 v32, v30, v30
	v_fmac_f32_e32 v19, v21, v21
	v_fmac_f32_e32 v32, v31, v31
	v_add_f32_e32 v19, v32, v19
	v_add_f32_e32 v18, v19, v18
	v_add_f32_e32 v32, v38, v18
	ds_bpermute_b32 v33, v114, v32
	v_lshl_add_u64 v[18:19], s[14:15], 0, v[88:89]
	global_store_dwordx4 v[18:19], v[26:29], off
	v_cvt_pk_bf16_f32 v18, v22, v23
	v_cvt_pk_bf16_f32 v19, v24, v25
	s_waitcnt lgkmcnt(0)
	v_add_f32_e32 v24, v32, v33
	ds_bpermute_b32 v25, v115, v24
	v_lshl_add_u64 v[22:23], s[14:15], 0, v[86:87]
	v_cvt_pk_bf16_f32 v20, v20, v21
	v_cvt_pk_bf16_f32 v21, v30, v31
	global_store_dwordx4 v[22:23], v[18:21], off
	s_waitcnt vmcnt(7)
	v_lshlrev_b32_e32 v22, 16, v72
	v_and_b32_e32 v23, 0xffff0000, v72
	s_waitcnt lgkmcnt(0)
	v_add_f32_e32 v18, v24, v25
	v_cndmask_b32_e64 v1, v1, v18, s[6:7]
	v_lshlrev_b32_e32 v18, 16, v70
	v_and_b32_e32 v19, 0xffff0000, v70
	v_lshlrev_b32_e32 v20, 16, v71
	v_and_b32_e32 v21, 0xffff0000, v71
	v_pk_add_f32 v[14:15], v[14:15], v[18:19]
	v_pk_add_f32 v[16:17], v[16:17], v[20:21]
	v_pk_add_f32 v[20:21], v[10:11], v[22:23]
	v_cvt_pk_bf16_f32 v10, v14, v15
	v_mul_f32_e32 v15, v15, v15
	v_lshlrev_b32_e32 v24, 16, v73
	v_and_b32_e32 v25, 0xffff0000, v73
	v_fmac_f32_e32 v15, v14, v14
	v_mul_f32_e32 v14, v16, v16
	v_pk_add_f32 v[18:19], v[12:13], v[24:25]
	v_fmac_f32_e32 v14, v17, v17
	v_cvt_pk_bf16_f32 v11, v16, v17
	v_add_f32_e32 v14, v15, v14
	v_mul_f32_e32 v15, v20, v20
	v_mul_f32_e32 v16, v18, v18
	v_fmac_f32_e32 v15, v21, v21
	v_fmac_f32_e32 v16, v19, v19
	v_add_f32_e32 v15, v16, v15
	v_add_f32_e32 v22, v15, v14
	s_waitcnt vmcnt(6)
	v_lshlrev_b32_e32 v14, 16, v66
	v_and_b32_e32 v15, 0xffff0000, v66
	v_lshlrev_b32_e32 v16, 16, v67
	v_and_b32_e32 v17, 0xffff0000, v67
	v_cvt_pk_bf16_f32 v12, v20, v21
	v_cvt_pk_bf16_f32 v13, v18, v19
	v_lshlrev_b32_e32 v18, 16, v68
	v_and_b32_e32 v19, 0xffff0000, v68
	v_lshlrev_b32_e32 v20, 16, v69
	v_and_b32_e32 v21, 0xffff0000, v69
	v_pk_add_f32 v[8:9], v[8:9], v[16:17]
	v_pk_add_f32 v[6:7], v[6:7], v[14:15]
	v_pk_add_f32 v[14:15], v[4:5], v[20:21]
	v_pk_add_f32 v[4:5], v[2:3], v[18:19]
	v_mul_f32_e32 v2, v7, v7
	v_mul_f32_e32 v3, v8, v8
	v_fmac_f32_e32 v2, v6, v6
	v_fmac_f32_e32 v3, v9, v9
	v_add_f32_e32 v2, v2, v3
	v_mul_f32_e32 v3, v4, v4
	v_mul_f32_e32 v16, v14, v14
	v_fmac_f32_e32 v3, v5, v5
	v_fmac_f32_e32 v16, v15, v15
	v_add_f32_e32 v3, v16, v3
	v_add_f32_e32 v2, v3, v2
	v_add_f32_e32 v16, v22, v2
	ds_bpermute_b32 v17, v114, v16
	v_lshl_add_u64 v[2:3], s[14:15], 0, v[84:85]
	global_store_dwordx4 v[2:3], v[10:13], off
	v_cvt_pk_bf16_f32 v2, v6, v7
	v_cvt_pk_bf16_f32 v3, v8, v9
	s_waitcnt lgkmcnt(0)
	v_add_f32_e32 v8, v16, v17
	ds_bpermute_b32 v9, v115, v8
	v_lshl_add_u64 v[6:7], s[14:15], 0, v[82:83]
	v_cvt_pk_bf16_f32 v4, v4, v5
	v_cvt_pk_bf16_f32 v5, v14, v15
	global_store_dwordx4 v[6:7], v[2:5], off
	s_waitcnt lgkmcnt(0)
	s_nop 0
	v_add_f32_e32 v2, v8, v9
	v_cndmask_b32_e64 v1, v1, v2, s[8:9]
	v_add_u32_e32 v2, 0x80, v162
	v_ashrrev_i32_e32 v3, 31, v2
	v_lshl_add_u64 v[2:3], v[2:3], 2, s[16:17]
	global_atomic_add_f32 v[2:3], v1, off
	s_cbranch_vccnz .LBB0_1400
	s_andn2_b64 vcc, exec, s[0:1]
	s_cbranch_vccnz .LBB0_1399
	s_barrier
	s_branch .LBB0_1399

.LBB0_1569:
	s_andn2_b64 vcc, exec, s[12:13]
	s_cbranch_vccnz .LBB0_1571
	v_lshl_add_u32 v146, s44, 8, v148
	v_lshl_or_b32 v144, s45, 8, v150
	v_ashrrev_i32_e32 v147, 31, v146
	v_ashrrev_i32_e32 v145, 31, v144
	v_lshlrev_b64 v[154:155], 11, v[146:147]
	v_or_b32_e32 v162, 16, v146
	v_lshl_add_u64 v[178:179], v[154:155], 0, v[144:145]
	v_ashrrev_i32_e32 v163, 31, v162
	v_lshlrev_b64 v[158:159], 1, v[178:179]
	v_lshlrev_b64 v[162:163], 11, v[162:163]
	v_lshl_add_u64 v[154:155], s[6:7], 0, v[158:159]
	v_or_b32_e32 v158, 0x100, v158
	v_lshl_add_u64 v[180:181], v[162:163], 0, v[144:145]
	v_lshl_add_u64 v[158:159], s[6:7], 0, v[158:159]
	v_lshlrev_b64 v[166:167], 1, v[180:181]
	global_load_dwordx4 v[154:157], v[154:155], off
	v_lshl_add_u64 v[162:163], s[6:7], 0, v[166:167]
	global_load_dwordx4 v[158:161], v[158:159], off
	v_or_b32_e32 v170, 32, v146
	global_load_dwordx4 v[162:165], v[162:163], off
	v_or_b32_e32 v166, 0x100, v166
	v_ashrrev_i32_e32 v171, 31, v170
	v_lshl_add_u64 v[166:167], s[6:7], 0, v[166:167]
	v_lshlrev_b64 v[170:171], 11, v[170:171]
	global_load_dwordx4 v[166:169], v[166:167], off
	v_lshl_add_u64 v[186:187], v[170:171], 0, v[144:145]
	v_lshlrev_b64 v[174:175], 1, v[186:187]
	v_lshl_add_u64 v[170:171], s[6:7], 0, v[174:175]
	v_or_b32_e32 v182, 48, v146
	global_load_dwordx4 v[170:173], v[170:171], off
	v_ashrrev_i32_e32 v183, 31, v182
	v_or_b32_e32 v174, 0x100, v174
	v_lshlrev_b64 v[182:183], 11, v[182:183]
	v_lshl_add_u64 v[174:175], s[6:7], 0, v[174:175]
	v_lshl_add_u64 v[188:189], v[182:183], 0, v[144:145]
	global_load_dwordx4 v[174:177], v[174:175], off
	v_lshl_add_u64 v[190:191], v[178:179], 2, s[50:51]
	v_lshlrev_b64 v[178:179], 1, v[188:189]
	v_lshl_add_u64 v[192:193], v[180:181], 2, s[50:51]
	v_or_b32_e32 v180, 0x100, v178
	v_mov_b32_e32 v181, v179
	v_lshl_add_u64 v[182:183], s[6:7], 0, v[178:179]
	v_lshl_add_u64 v[178:179], s[6:7], 0, v[180:181]
	global_load_dwordx4 v[178:181], v[178:179], off
	s_nop 0
	global_load_dwordx4 v[182:185], v[182:183], off
	s_waitcnt vmcnt(7)
	v_lshlrev_b32_e32 v196, 16, v154
	v_and_b32_e32 v197, 0xffff0000, v154
	v_lshlrev_b32_e32 v154, 16, v155
	v_and_b32_e32 v155, 0xffff0000, v155
	s_waitcnt vmcnt(6)
	v_lshlrev_b32_e32 v198, 16, v160
	v_and_b32_e32 v199, 0xffff0000, v160
	v_lshlrev_b32_e32 v160, 16, v161
	v_and_b32_e32 v161, 0xffff0000, v161
	v_lshlrev_b32_e32 v200, 16, v158
	v_and_b32_e32 v201, 0xffff0000, v158
	v_lshlrev_b32_e32 v158, 16, v159
	v_and_b32_e32 v159, 0xffff0000, v159
	v_lshlrev_b32_e32 v194, 16, v156
	v_and_b32_e32 v195, 0xffff0000, v156
	v_lshlrev_b32_e32 v156, 16, v157
	v_and_b32_e32 v157, 0xffff0000, v157
	v_pk_fma_f32 v[126:127], v[126:127], 0.5, v[154:155] op_sel_hi:[1,0,1]
	v_pk_fma_f32 v[114:115], v[114:115], 0.5, v[160:161] op_sel_hi:[1,0,1]
	v_pk_fma_f32 v[118:119], v[118:119], 0.5, v[158:159] op_sel_hi:[1,0,1]
	s_waitcnt vmcnt(5)
	v_lshlrev_b32_e32 v154, 16, v164
	v_and_b32_e32 v155, 0xffff0000, v164
	v_lshlrev_b32_e32 v158, 16, v162
	v_and_b32_e32 v159, 0xffff0000, v162
	v_lshlrev_b32_e32 v160, 16, v163
	v_and_b32_e32 v161, 0xffff0000, v163
	v_pk_fma_f32 v[122:123], v[122:123], 0.5, v[156:157] op_sel_hi:[1,0,1]
	v_pk_fma_f32 v[124:125], v[124:125], 0.5, v[196:197] op_sel_hi:[1,0,1]
	v_lshlrev_b32_e32 v156, 16, v165
	v_and_b32_e32 v157, 0xffff0000, v165
	v_pk_fma_f32 v[104:105], v[104:105], 0.5, v[154:155] op_sel_hi:[1,0,1]
	v_pk_fma_f32 v[110:111], v[110:111], 0.5, v[160:161] op_sel_hi:[1,0,1]
	v_pk_fma_f32 v[108:109], v[108:109], 0.5, v[158:159] op_sel_hi:[1,0,1]
	v_pk_fma_f32 v[120:121], v[120:121], 0.5, v[194:195] op_sel_hi:[1,0,1]
	v_pk_fma_f32 v[112:113], v[112:113], 0.5, v[198:199] op_sel_hi:[1,0,1]
	v_pk_fma_f32 v[116:117], v[116:117], 0.5, v[200:201] op_sel_hi:[1,0,1]
	global_store_dwordx4 v[190:191], v[124:127], off
	global_store_dwordx4 v[190:191], v[120:123], off offset:16
	global_store_dwordx4 v[190:191], v[116:119], off offset:512
	global_store_dwordx4 v[190:191], v[112:115], off offset:528
	v_pk_fma_f32 v[106:107], v[106:107], 0.5, v[156:157] op_sel_hi:[1,0,1]
	global_store_dwordx4 v[192:193], v[108:111], off
	global_store_dwordx4 v[192:193], v[104:107], off offset:16
	s_waitcnt vmcnt(10)
	v_lshlrev_b32_e32 v162, 16, v168
	v_and_b32_e32 v163, 0xffff0000, v168
	v_lshlrev_b32_e32 v104, 16, v169
	v_and_b32_e32 v105, 0xffff0000, v169
	v_pk_fma_f32 v[102:103], v[102:103], 0.5, v[104:105] op_sel_hi:[1,0,1]
	v_lshlrev_b32_e32 v104, 16, v166
	v_and_b32_e32 v105, 0xffff0000, v166
	v_lshlrev_b32_e32 v106, 16, v167
	v_and_b32_e32 v107, 0xffff0000, v167
	v_pk_fma_f32 v[100:101], v[100:101], 0.5, v[162:163] op_sel_hi:[1,0,1]
	v_pk_fma_f32 v[98:99], v[98:99], 0.5, v[106:107] op_sel_hi:[1,0,1]
	v_pk_fma_f32 v[96:97], v[96:97], 0.5, v[104:105] op_sel_hi:[1,0,1]
	global_store_dwordx4 v[192:193], v[96:99], off offset:512
	global_store_dwordx4 v[192:193], v[100:103], off offset:528
	s_nop 0
	s_waitcnt vmcnt(11)
	v_lshlrev_b32_e32 v98, 16, v172
	v_and_b32_e32 v99, 0xffff0000, v172
	v_lshlrev_b32_e32 v100, 16, v173
	v_and_b32_e32 v101, 0xffff0000, v173
	v_pk_fma_f32 v[94:95], v[94:95], 0.5, v[100:101] op_sel_hi:[1,0,1]
	v_pk_fma_f32 v[92:93], v[92:93], 0.5, v[98:99] op_sel_hi:[1,0,1]
	v_lshlrev_b32_e32 v98, 16, v170
	v_and_b32_e32 v99, 0xffff0000, v170
	v_lshlrev_b32_e32 v100, 16, v171
	v_and_b32_e32 v101, 0xffff0000, v171
	v_lshl_add_u64 v[96:97], v[186:187], 2, s[50:51]
	v_pk_fma_f32 v[90:91], v[90:91], 0.5, v[100:101] op_sel_hi:[1,0,1]
	v_pk_fma_f32 v[88:89], v[88:89], 0.5, v[98:99] op_sel_hi:[1,0,1]
	global_store_dwordx4 v[96:97], v[88:91], off
	global_store_dwordx4 v[96:97], v[92:95], off offset:16
	s_nop 0
	s_waitcnt vmcnt(12)
	v_lshlrev_b32_e32 v88, 16, v176
	v_and_b32_e32 v89, 0xffff0000, v176
	v_lshlrev_b32_e32 v90, 16, v177
	v_and_b32_e32 v91, 0xffff0000, v177
	v_pk_fma_f32 v[86:87], v[86:87], 0.5, v[90:91] op_sel_hi:[1,0,1]
	v_pk_fma_f32 v[84:85], v[84:85], 0.5, v[88:89] op_sel_hi:[1,0,1]
	v_lshlrev_b32_e32 v88, 16, v174
	v_and_b32_e32 v89, 0xffff0000, v174
	v_lshlrev_b32_e32 v90, 16, v175
	v_and_b32_e32 v91, 0xffff0000, v175
	v_pk_fma_f32 v[82:83], v[82:83], 0.5, v[90:91] op_sel_hi:[1,0,1]
	v_pk_fma_f32 v[80:81], v[80:81], 0.5, v[88:89] op_sel_hi:[1,0,1]
	global_store_dwordx4 v[96:97], v[80:83], off offset:512
	global_store_dwordx4 v[96:97], v[84:87], off offset:528
	s_nop 0
	s_waitcnt vmcnt(12)
	v_lshlrev_b32_e32 v82, 16, v184
	v_and_b32_e32 v83, 0xffff0000, v184
	v_lshlrev_b32_e32 v84, 16, v185
	v_and_b32_e32 v85, 0xffff0000, v185
	v_pk_fma_f32 v[78:79], v[78:79], 0.5, v[84:85] op_sel_hi:[1,0,1]
	v_pk_fma_f32 v[76:77], v[76:77], 0.5, v[82:83] op_sel_hi:[1,0,1]
	v_lshlrev_b32_e32 v82, 16, v182
	v_and_b32_e32 v83, 0xffff0000, v182
	v_lshlrev_b32_e32 v84, 16, v183
	v_and_b32_e32 v85, 0xffff0000, v183
	v_lshl_add_u64 v[80:81], v[188:189], 2, s[50:51]
	v_pk_fma_f32 v[74:75], v[74:75], 0.5, v[84:85] op_sel_hi:[1,0,1]
	v_pk_fma_f32 v[72:73], v[72:73], 0.5, v[82:83] op_sel_hi:[1,0,1]
	global_store_dwordx4 v[80:81], v[72:75], off
	global_store_dwordx4 v[80:81], v[76:79], off offset:16
	s_nop 0
	v_lshlrev_b32_e32 v72, 16, v180
	v_and_b32_e32 v73, 0xffff0000, v180
	v_lshlrev_b32_e32 v74, 16, v181
	v_and_b32_e32 v75, 0xffff0000, v181
	v_pk_fma_f32 v[70:71], v[70:71], 0.5, v[74:75] op_sel_hi:[1,0,1]
	v_pk_fma_f32 v[68:69], v[68:69], 0.5, v[72:73] op_sel_hi:[1,0,1]
	v_lshlrev_b32_e32 v72, 16, v178
	v_and_b32_e32 v73, 0xffff0000, v178
	v_lshlrev_b32_e32 v74, 16, v179
	v_and_b32_e32 v75, 0xffff0000, v179
	v_pk_fma_f32 v[66:67], v[66:67], 0.5, v[74:75] op_sel_hi:[1,0,1]
	v_pk_fma_f32 v[64:65], v[64:65], 0.5, v[72:73] op_sel_hi:[1,0,1]
	global_store_dwordx4 v[80:81], v[64:67], off offset:512
	global_store_dwordx4 v[80:81], v[68:71], off offset:528
	s_nop 0
	v_add_u32_e32 v64, 0x80, v146
	v_ashrrev_i32_e32 v65, 31, v64
	v_lshlrev_b64 v[64:65], 11, v[64:65]
	v_lshl_add_u64 v[96:97], v[64:65], 0, v[144:145]
	v_lshlrev_b64 v[64:65], 1, v[96:97]
	v_lshl_add_u64 v[66:67], s[6:7], 0, v[64:65]
	v_or_b32_e32 v64, 0x100, v64
	v_lshl_add_u64 v[64:65], s[6:7], 0, v[64:65]
	global_load_dwordx4 v[68:71], v[66:67], off
	global_load_dwordx4 v[72:75], v[64:65], off
	v_add_u32_e32 v64, 0x90, v146
	v_ashrrev_i32_e32 v65, 31, v64
	v_lshlrev_b64 v[64:65], 11, v[64:65]
	v_lshl_add_u64 v[98:99], v[64:65], 0, v[144:145]
	v_lshlrev_b64 v[64:65], 1, v[98:99]
	v_lshl_add_u64 v[66:67], s[6:7], 0, v[64:65]
	v_or_b32_e32 v64, 0x100, v64
	v_lshl_add_u64 v[64:65], s[6:7], 0, v[64:65]
	global_load_dwordx4 v[76:79], v[66:67], off
	global_load_dwordx4 v[80:83], v[64:65], off
	v_add_u32_e32 v64, 0xa0, v146
	v_ashrrev_i32_e32 v65, 31, v64
	v_lshlrev_b64 v[64:65], 11, v[64:65]
	v_lshl_add_u64 v[100:101], v[64:65], 0, v[144:145]
	v_lshlrev_b64 v[64:65], 1, v[100:101]
	v_lshl_add_u64 v[66:67], s[6:7], 0, v[64:65]
	v_or_b32_e32 v64, 0x100, v64
	v_lshl_add_u64 v[64:65], s[6:7], 0, v[64:65]
	global_load_dwordx4 v[84:87], v[66:67], off
	global_load_dwordx4 v[88:91], v[64:65], off
	v_add_u32_e32 v64, 0xb0, v146
	v_ashrrev_i32_e32 v65, 31, v64
	v_lshlrev_b64 v[64:65], 11, v[64:65]
	v_lshl_add_u64 v[102:103], v[64:65], 0, v[144:145]
	v_lshlrev_b64 v[64:65], 1, v[102:103]
	v_or_b32_e32 v66, 0x100, v64
	v_mov_b32_e32 v67, v65
	v_lshl_add_u64 v[66:67], s[6:7], 0, v[66:67]
	v_lshl_add_u64 v[92:93], s[6:7], 0, v[64:65]
	global_load_dwordx4 v[64:67], v[66:67], off
	s_nop 0
	global_load_dwordx4 v[92:95], v[92:93], off
	v_lshl_add_u64 v[96:97], v[96:97], 2, s[50:51]
	s_waitcnt vmcnt(7)
	v_lshlrev_b32_e32 v104, 16, v70
	v_and_b32_e32 v105, 0xffff0000, v70
	v_lshlrev_b32_e32 v70, 16, v71
	v_and_b32_e32 v71, 0xffff0000, v71
	v_pk_fma_f32 v[62:63], v[62:63], 0.5, v[70:71] op_sel_hi:[1,0,1]
	v_lshlrev_b32_e32 v70, 16, v68
	v_and_b32_e32 v71, 0xffff0000, v68
	v_lshlrev_b32_e32 v68, 16, v69
	v_and_b32_e32 v69, 0xffff0000, v69
	v_pk_fma_f32 v[58:59], v[58:59], 0.5, v[68:69] op_sel_hi:[1,0,1]
	v_pk_fma_f32 v[56:57], v[56:57], 0.5, v[70:71] op_sel_hi:[1,0,1]
	v_pk_fma_f32 v[60:61], v[60:61], 0.5, v[104:105] op_sel_hi:[1,0,1]
	global_store_dwordx4 v[96:97], v[56:59], off
	global_store_dwordx4 v[96:97], v[60:63], off offset:16
	s_waitcnt vmcnt(8)
	v_lshlrev_b32_e32 v56, 16, v74
	v_and_b32_e32 v57, 0xffff0000, v74
	v_lshlrev_b32_e32 v58, 16, v75
	v_and_b32_e32 v59, 0xffff0000, v75
	v_pk_fma_f32 v[54:55], v[54:55], 0.5, v[58:59] op_sel_hi:[1,0,1]
	v_pk_fma_f32 v[52:53], v[52:53], 0.5, v[56:57] op_sel_hi:[1,0,1]
	v_lshlrev_b32_e32 v56, 16, v72
	v_and_b32_e32 v57, 0xffff0000, v72
	v_lshlrev_b32_e32 v58, 16, v73
	v_and_b32_e32 v59, 0xffff0000, v73
	v_pk_fma_f32 v[50:51], v[50:51], 0.5, v[58:59] op_sel_hi:[1,0,1]
	v_pk_fma_f32 v[48:49], v[48:49], 0.5, v[56:57] op_sel_hi:[1,0,1]
	global_store_dwordx4 v[96:97], v[48:51], off offset:512
	global_store_dwordx4 v[96:97], v[52:55], off offset:528
	s_waitcnt vmcnt(9)
	v_lshlrev_b32_e32 v50, 16, v78
	v_and_b32_e32 v51, 0xffff0000, v78
	v_lshlrev_b32_e32 v52, 16, v79
	v_and_b32_e32 v53, 0xffff0000, v79
	v_pk_fma_f32 v[46:47], v[46:47], 0.5, v[52:53] op_sel_hi:[1,0,1]
	v_pk_fma_f32 v[44:45], v[44:45], 0.5, v[50:51] op_sel_hi:[1,0,1]
	v_lshlrev_b32_e32 v50, 16, v76
	v_and_b32_e32 v51, 0xffff0000, v76
	v_lshlrev_b32_e32 v52, 16, v77
	v_and_b32_e32 v53, 0xffff0000, v77
	v_lshl_add_u64 v[48:49], v[98:99], 2, s[50:51]
	v_pk_fma_f32 v[42:43], v[42:43], 0.5, v[52:53] op_sel_hi:[1,0,1]
	v_pk_fma_f32 v[40:41], v[40:41], 0.5, v[50:51] op_sel_hi:[1,0,1]
	global_store_dwordx4 v[48:49], v[40:43], off
	global_store_dwordx4 v[48:49], v[44:47], off offset:16
	s_waitcnt vmcnt(10)
	v_lshlrev_b32_e32 v40, 16, v82
	v_and_b32_e32 v41, 0xffff0000, v82
	v_lshlrev_b32_e32 v42, 16, v83
	v_and_b32_e32 v43, 0xffff0000, v83
	v_pk_fma_f32 v[38:39], v[38:39], 0.5, v[42:43] op_sel_hi:[1,0,1]
	v_pk_fma_f32 v[36:37], v[36:37], 0.5, v[40:41] op_sel_hi:[1,0,1]
	v_lshlrev_b32_e32 v40, 16, v80
	v_and_b32_e32 v41, 0xffff0000, v80
	v_lshlrev_b32_e32 v42, 16, v81
	v_and_b32_e32 v43, 0xffff0000, v81
	v_pk_fma_f32 v[34:35], v[34:35], 0.5, v[42:43] op_sel_hi:[1,0,1]
	v_pk_fma_f32 v[32:33], v[32:33], 0.5, v[40:41] op_sel_hi:[1,0,1]
	global_store_dwordx4 v[48:49], v[32:35], off offset:512
	global_store_dwordx4 v[48:49], v[36:39], off offset:528
	s_waitcnt vmcnt(11)
	v_lshlrev_b32_e32 v34, 16, v86
	v_and_b32_e32 v35, 0xffff0000, v86
	v_lshlrev_b32_e32 v36, 16, v87
	v_and_b32_e32 v37, 0xffff0000, v87
	v_pk_fma_f32 v[30:31], v[30:31], 0.5, v[36:37] op_sel_hi:[1,0,1]
	v_pk_fma_f32 v[28:29], v[28:29], 0.5, v[34:35] op_sel_hi:[1,0,1]
	v_lshlrev_b32_e32 v34, 16, v84
	v_and_b32_e32 v35, 0xffff0000, v84
	v_lshlrev_b32_e32 v36, 16, v85
	v_and_b32_e32 v37, 0xffff0000, v85
	v_lshl_add_u64 v[32:33], v[100:101], 2, s[50:51]
	v_pk_fma_f32 v[26:27], v[26:27], 0.5, v[36:37] op_sel_hi:[1,0,1]
	v_pk_fma_f32 v[24:25], v[24:25], 0.5, v[34:35] op_sel_hi:[1,0,1]
	global_store_dwordx4 v[32:33], v[24:27], off
	global_store_dwordx4 v[32:33], v[28:31], off offset:16
	s_waitcnt vmcnt(12)
	v_lshlrev_b32_e32 v24, 16, v90
	v_and_b32_e32 v25, 0xffff0000, v90
	v_lshlrev_b32_e32 v26, 16, v91
	v_and_b32_e32 v27, 0xffff0000, v91
	v_pk_fma_f32 v[22:23], v[22:23], 0.5, v[26:27] op_sel_hi:[1,0,1]
	v_pk_fma_f32 v[20:21], v[20:21], 0.5, v[24:25] op_sel_hi:[1,0,1]
	v_lshlrev_b32_e32 v24, 16, v88
	v_and_b32_e32 v25, 0xffff0000, v88
	v_lshlrev_b32_e32 v26, 16, v89
	v_and_b32_e32 v27, 0xffff0000, v89
	v_pk_fma_f32 v[18:19], v[18:19], 0.5, v[26:27] op_sel_hi:[1,0,1]
	v_pk_fma_f32 v[16:17], v[16:17], 0.5, v[24:25] op_sel_hi:[1,0,1]
	global_store_dwordx4 v[32:33], v[16:19], off offset:512
	global_store_dwordx4 v[32:33], v[20:23], off offset:528
	s_waitcnt vmcnt(12)
	v_lshlrev_b32_e32 v18, 16, v94
	v_and_b32_e32 v19, 0xffff0000, v94
	v_lshlrev_b32_e32 v20, 16, v95
	v_and_b32_e32 v21, 0xffff0000, v95
	v_pk_fma_f32 v[14:15], v[14:15], 0.5, v[20:21] op_sel_hi:[1,0,1]
	v_pk_fma_f32 v[12:13], v[12:13], 0.5, v[18:19] op_sel_hi:[1,0,1]
	v_lshlrev_b32_e32 v18, 16, v92
	v_and_b32_e32 v19, 0xffff0000, v92
	v_lshlrev_b32_e32 v20, 16, v93
	v_and_b32_e32 v21, 0xffff0000, v93
	v_lshl_add_u64 v[16:17], v[102:103], 2, s[50:51]
	v_pk_fma_f32 v[10:11], v[10:11], 0.5, v[20:21] op_sel_hi:[1,0,1]
	v_pk_fma_f32 v[8:9], v[8:9], 0.5, v[18:19] op_sel_hi:[1,0,1]
	global_store_dwordx4 v[16:17], v[8:11], off
	global_store_dwordx4 v[16:17], v[12:15], off offset:16
	s_nop 0
	v_lshlrev_b32_e32 v8, 16, v66
	v_and_b32_e32 v9, 0xffff0000, v66
	v_lshlrev_b32_e32 v10, 16, v67
	v_and_b32_e32 v11, 0xffff0000, v67
	v_pk_fma_f32 v[6:7], v[6:7], 0.5, v[10:11] op_sel_hi:[1,0,1]
	v_pk_fma_f32 v[4:5], v[4:5], 0.5, v[8:9] op_sel_hi:[1,0,1]
	v_lshlrev_b32_e32 v8, 16, v64
	v_and_b32_e32 v9, 0xffff0000, v64
	v_lshlrev_b32_e32 v10, 16, v65
	v_and_b32_e32 v11, 0xffff0000, v65
	v_pk_fma_f32 v[2:3], v[2:3], 0.5, v[10:11] op_sel_hi:[1,0,1]
	v_pk_fma_f32 v[0:1], v[0:1], 0.5, v[8:9] op_sel_hi:[1,0,1]
	global_store_dwordx4 v[16:17], v[0:3], off offset:512
	global_store_dwordx4 v[16:17], v[4:7], off offset:528
